# GEMM loops: M0 setup reordered to drop s_nop before LDS-DMA; s_setprio 1 issued before the pre-MFMA barrier
# baseline (speedup 1.0000x reference)
; #define PG8_STAGE(bufoff, gbase, voff) do { _Pragma("unroll") for (int _i = 0; _i < 2; ++_i) \
;         __builtin_amdgcn_global_load_lds((const unsigned*)((const char*)(gbase) + (voff)[_i]), (LAS unsigned*)(lds + (bufoff) + ldsw + _i * 8192), 16, 0, 0); } while (0)
; #define PG8_LDA(dst, b, h) do { _Pragma("unroll") for (int m = 0; m < 4; ++m) _Pragma("unroll") for (int k = 0; k < 2; ++k) dst[m][k] = *(const LAS bf16x8*)(lds + PG8_SA(b, h) + aoff + m * 2048 + k * 1024); } while (0)
; #define PG8_LDB(dst, b, h) do { _Pragma("unroll") for (int n = 0; n < 2; ++n) _Pragma("unroll") for (int k = 0; k < 2; ++k) dst[n][k] = *(const LAS bf16x8*)(lds + PG8_SB(b, h) + boff + n * 2048 + k * 1024); } while (0)
; #define PG8_MMA(ai, bj, At, Bt) do { __builtin_amdgcn_s_setprio(1); _Pragma("unroll") for (int m = 0; m < 4; ++m) _Pragma("unroll") for (int n = 0; n < 2; ++n) _Pragma("unroll") for (int k = 0; k < 2; ++k) \
;         acc[ai][bj][m][n] = __builtin_amdgcn_mfma_f32_16x16x32_bf16(Bt[n][k], At[m][k], acc[ai][bj][m][n], 0, 0, 0); __builtin_amdgcn_s_setprio(0); } while (0)
; #define PG8_WAIT_L(n) asm volatile("s_waitcnt lgkmcnt(" #n ")" ::: "memory")
; #define PG8_BAR __builtin_amdgcn_s_barrier()
; #define PG8_SCHED __builtin_amdgcn_sched_barrier(0)
; template <class Epi, class Sched>
; DI void gemm_phase(LAS unsigned char* lds, const Gemm g, const Sched& S, const Epi& E) {
;     ...
;             PG8_LDB(B0, 0, 0); PG8_SCHED; PG8_LDA(At, 0, 0); PG8_STAGE(PG8_SA(1, 1), a1 + hstep, voffA);
;             PG8_WAIT_L(8); PG8_BAR; PG8_WAIT_L(0); PG8_MMA(0, 0, At, B0); PG8_BAR; PG8_SCHED;
;             PG8_LDB(B1, 0, 1); PG8_STAGE(PG8_SB(0, 0), b2, voffB);
;             PG8_BAR; PG8_WAIT_L(0); PG8_MMA(0, 1, At, B1); PG8_BAR;
;             PG8_LDA(At, 0, 1); PG8_STAGE(PG8_SA(0, 0), a2, voffA);
;             PG8_BAR; PG8_WAIT_L(0); PG8_MMA(1, 0, At, B0); PG8_BAR; PG8_SCHED;
.LBB0_503:
	s_add_u32 s14, s8, 0xfffc0080
	s_addc_u32 s15, s9, -1
	s_add_i32 s75, 0, 0x10000
	v_add_u32_e32 v128, s75, v146
	ds_read_b128 v[140:143], v128
	ds_read_b128 v[178:181], v128 offset:1024
	ds_read_b128 v[182:185], v128 offset:2048
	ds_read_b128 v[186:189], v128 offset:3072
	s_cmp_eq_u32 s41, 12
	s_cselect_b32 s17, s11, s15
	s_cselect_b32 s16, s13, s14
	s_cselect_b32 s15, s35, s40
	s_cselect_b32 s14, s38, s39
	v_lshl_add_u64 v[144:145], s[8:9], 0, v[136:137]
	s_add_i32 m0, s66, 0xc000
	ds_read_b128 v[190:193], v148
	ds_read_b128 v[194:197], v148 offset:1024
	ds_read_b128 v[198:201], v148 offset:2048
	ds_read_b128 v[202:205], v148 offset:3072
	ds_read_b128 v[206:209], v148 offset:4096
	ds_read_b128 v[210:213], v148 offset:5120
	ds_read_b128 v[214:217], v148 offset:6144
	ds_read_b128 v[218:221], v148 offset:7168
	global_load_lds_dwordx4 v[144:145], off
	s_add_i32 m0, s66, 0xe000
	v_lshl_add_u64 v[144:145], s[8:9], 0, v[138:139]
	global_load_lds_dwordx4 v[144:145], off
	s_waitcnt lgkmcnt(8)
	s_setprio 1
	s_barrier
	s_waitcnt lgkmcnt(0)
	v_mfma_f32_16x16x32_bf16 v[124:127], v[140:143], v[190:193], v[124:127]
	v_mfma_f32_16x16x32_bf16 v[120:123], v[182:185], v[190:193], v[120:123]
	v_mfma_f32_16x16x32_bf16 v[108:111], v[140:143], v[198:201], v[108:111]
	v_mfma_f32_16x16x32_bf16 v[104:107], v[182:185], v[198:201], v[104:107]
	v_mfma_f32_16x16x32_bf16 v[92:95], v[140:143], v[206:209], v[92:95]
	v_mfma_f32_16x16x32_bf16 v[88:91], v[182:185], v[206:209], v[88:91]
	v_mfma_f32_16x16x32_bf16 v[76:79], v[140:143], v[214:217], v[76:79]
	v_mfma_f32_16x16x32_bf16 v[72:75], v[182:185], v[214:217], v[72:75]
	v_mfma_f32_16x16x32_bf16 v[124:127], v[178:181], v[194:197], v[124:127]
	v_mfma_f32_16x16x32_bf16 v[120:123], v[186:189], v[194:197], v[120:123]
	v_mfma_f32_16x16x32_bf16 v[108:111], v[178:181], v[202:205], v[108:111]
	v_mfma_f32_16x16x32_bf16 v[104:107], v[186:189], v[202:205], v[104:107]
	v_mfma_f32_16x16x32_bf16 v[92:95], v[178:181], v[210:213], v[92:95]
	v_mfma_f32_16x16x32_bf16 v[88:91], v[186:189], v[210:213], v[88:91]
	v_mfma_f32_16x16x32_bf16 v[76:79], v[178:181], v[218:221], v[76:79]
	v_mfma_f32_16x16x32_bf16 v[72:75], v[186:189], v[218:221], v[72:75]
	s_setprio 0
	s_barrier
	s_add_i32 s81, 0, 0x14000
	s_add_i32 s75, s75, s65
	v_add_u32_e32 v128, s81, v146
	v_lshl_add_u64 v[144:145], s[14:15], 0, v[132:133]
	s_mov_b32 m0, s75
	ds_read_b128 v[222:225], v128
	ds_read_b128 v[226:229], v128 offset:1024
	ds_read_b128 v[230:233], v128 offset:2048
	ds_read_b128 v[234:237], v128 offset:3072
	global_load_lds_dwordx4 v[144:145], off
	s_add_i32 m0, s75, 0x2000
	v_lshl_add_u64 v[150:151], s[14:15], 0, v[134:135]
	global_load_lds_dwordx4 v[150:151], off
	s_setprio 1
	s_barrier
	s_waitcnt lgkmcnt(0)
	v_mfma_f32_16x16x32_bf16 v[116:119], v[222:225], v[190:193], v[116:119]
	v_mfma_f32_16x16x32_bf16 v[112:115], v[230:233], v[190:193], v[112:115]
	v_mfma_f32_16x16x32_bf16 v[100:103], v[222:225], v[198:201], v[100:103]
	v_mfma_f32_16x16x32_bf16 v[96:99], v[230:233], v[198:201], v[96:99]
	v_mfma_f32_16x16x32_bf16 v[84:87], v[222:225], v[206:209], v[84:87]
	v_mfma_f32_16x16x32_bf16 v[80:83], v[230:233], v[206:209], v[80:83]
	v_mfma_f32_16x16x32_bf16 v[68:71], v[222:225], v[214:217], v[68:71]
	v_mfma_f32_16x16x32_bf16 v[64:67], v[230:233], v[214:217], v[64:67]
	v_mfma_f32_16x16x32_bf16 v[116:119], v[226:229], v[194:197], v[116:119]
	v_mfma_f32_16x16x32_bf16 v[112:115], v[234:237], v[194:197], v[112:115]
	v_mfma_f32_16x16x32_bf16 v[100:103], v[226:229], v[202:205], v[100:103]
	v_mfma_f32_16x16x32_bf16 v[96:99], v[234:237], v[202:205], v[96:99]
	v_mfma_f32_16x16x32_bf16 v[84:87], v[226:229], v[210:213], v[84:87]
	v_mfma_f32_16x16x32_bf16 v[80:83], v[234:237], v[210:213], v[80:83]
	v_mfma_f32_16x16x32_bf16 v[68:71], v[226:229], v[218:221], v[68:71]
	v_mfma_f32_16x16x32_bf16 v[64:67], v[234:237], v[218:221], v[64:67]
	s_setprio 0
	s_mov_b32 m0, s66
	v_lshl_add_u64 v[162:163], s[16:17], 0, v[132:133]
	s_barrier
	ds_read_b128 v[190:193], v148 offset:16384
	ds_read_b128 v[194:197], v148 offset:17408
	ds_read_b128 v[198:201], v148 offset:18432
	ds_read_b128 v[202:205], v148 offset:19456
	ds_read_b128 v[206:209], v148 offset:20480
	ds_read_b128 v[210:213], v148 offset:21504
	ds_read_b128 v[214:217], v148 offset:22528
	ds_read_b128 v[218:221], v148 offset:23552
	global_load_lds_dwordx4 v[162:163], off
	s_mov_b32 m0, s67
	v_lshl_add_u64 v[238:239], s[16:17], 0, v[134:135]
	global_load_lds_dwordx4 v[238:239], off
	s_setprio 1
	s_barrier
	s_waitcnt lgkmcnt(0)
	v_mfma_f32_16x16x32_bf16 v[60:63], v[140:143], v[190:193], v[60:63]
	v_mfma_f32_16x16x32_bf16 v[56:59], v[182:185], v[190:193], v[56:59]
	v_mfma_f32_16x16x32_bf16 v[44:47], v[140:143], v[198:201], v[44:47]
	v_mfma_f32_16x16x32_bf16 v[40:43], v[182:185], v[198:201], v[40:43]
	v_mfma_f32_16x16x32_bf16 v[28:31], v[140:143], v[206:209], v[28:31]
	v_mfma_f32_16x16x32_bf16 v[24:27], v[182:185], v[206:209], v[24:27]
	v_mfma_f32_16x16x32_bf16 v[12:15], v[140:143], v[214:217], v[12:15]
	v_mfma_f32_16x16x32_bf16 v[8:11], v[182:185], v[214:217], v[8:11]
	v_mfma_f32_16x16x32_bf16 v[60:63], v[178:181], v[194:197], v[60:63]
	v_mfma_f32_16x16x32_bf16 v[56:59], v[186:189], v[194:197], v[56:59]
	v_mfma_f32_16x16x32_bf16 v[44:47], v[178:181], v[202:205], v[44:47]
	v_mfma_f32_16x16x32_bf16 v[40:43], v[186:189], v[202:205], v[40:43]
	v_mfma_f32_16x16x32_bf16 v[28:31], v[178:181], v[210:213], v[28:31]
	v_mfma_f32_16x16x32_bf16 v[24:27], v[186:189], v[210:213], v[24:27]
	v_mfma_f32_16x16x32_bf16 v[12:15], v[178:181], v[218:221], v[12:15]
	v_mfma_f32_16x16x32_bf16 v[8:11], v[186:189], v[218:221], v[8:11]
	s_setprio 0
	s_barrier
; #define PG8_STAGE(bufoff, gbase, voff) do { _Pragma("unroll") for (int _i = 0; _i < 2; ++_i) \
;         __builtin_amdgcn_global_load_lds((const unsigned*)((const char*)(gbase) + (voff)[_i]), (LAS unsigned*)(lds + (bufoff) + ldsw + _i * 8192), 16, 0, 0); } while (0)
; #define PG8_LDA(dst, b, h) do { _Pragma("unroll") for (int m = 0; m < 4; ++m) _Pragma("unroll") for (int k = 0; k < 2; ++k) dst[m][k] = *(const LAS bf16x8*)(lds + PG8_SA(b, h) + aoff + m * 2048 + k * 1024); } while (0)
; #define PG8_LDB(dst, b, h) do { _Pragma("unroll") for (int n = 0; n < 2; ++n) _Pragma("unroll") for (int k = 0; k < 2; ++k) dst[n][k] = *(const LAS bf16x8*)(lds + PG8_SB(b, h) + boff + n * 2048 + k * 1024); } while (0)
; #define PG8_MMA(ai, bj, At, Bt) do { __builtin_amdgcn_s_setprio(1); _Pragma("unroll") for (int m = 0; m < 4; ++m) _Pragma("unroll") for (int n = 0; n < 2; ++n) _Pragma("unroll") for (int k = 0; k < 2; ++k) \
;         acc[ai][bj][m][n] = __builtin_amdgcn_mfma_f32_16x16x32_bf16(Bt[n][k], At[m][k], acc[ai][bj][m][n], 0, 0, 0); __builtin_amdgcn_s_setprio(0); } while (0)
; #define PG8_WAIT_V(n) asm volatile("s_waitcnt vmcnt(" #n ")" ::: "memory")
; #define PG8_WAIT_L(n) asm volatile("s_waitcnt lgkmcnt(" #n ")" ::: "memory")
; #define PG8_BAR __builtin_amdgcn_s_barrier()
; #define PG8_SCHED __builtin_amdgcn_sched_barrier(0)
; template <class Epi, class Sched>
; DI void gemm_phase(LAS unsigned char* lds, const Gemm g, const Sched& S, const Epi& E) {
;     ...
;             PG8_STAGE(PG8_SB(0, 1), b2 + hstep, voffB);
;             PG8_WAIT_V(6); PG8_BAR; PG8_MMA(1, 1, At, B1); PG8_BAR;
;             PG8_LDB(B0, 1, 0); PG8_SCHED; PG8_LDA(At, 1, 0); PG8_STAGE(PG8_SA(0, 1), a2 + hstep, voffA);
;             PG8_WAIT_L(8); PG8_BAR; PG8_WAIT_L(0); PG8_MMA(0, 0, At, B0); PG8_BAR; PG8_SCHED;
;             PG8_LDB(B1, 1, 1); PG8_STAGE(PG8_SB(1, 0), b3, voffB);
;             PG8_BAR; PG8_WAIT_L(0); PG8_MMA(0, 1, At, B1); PG8_BAR;
	s_add_u32 s92, s14, 0x40000
	s_addc_u32 s93, s15, 0
	s_add_i32 s75, s81, s65
	s_mov_b32 m0, s75
	v_lshl_add_u64 v[140:141], s[92:93], 0, v[132:133]
	global_load_lds_dwordx4 v[140:141], off
	s_add_i32 m0, s75, 0x2000
	v_lshl_add_u64 v[140:141], s[92:93], 0, v[134:135]
	global_load_lds_dwordx4 v[140:141], off
	s_waitcnt vmcnt(6)
	s_setprio 1
	s_barrier
	v_mfma_f32_16x16x32_bf16 v[52:55], v[222:225], v[190:193], v[52:55]
	v_mfma_f32_16x16x32_bf16 v[48:51], v[230:233], v[190:193], v[48:51]
	v_mfma_f32_16x16x32_bf16 v[36:39], v[222:225], v[198:201], v[36:39]
	v_mfma_f32_16x16x32_bf16 v[32:35], v[230:233], v[198:201], v[32:35]
	v_mfma_f32_16x16x32_bf16 v[20:23], v[222:225], v[206:209], v[20:23]
	v_mfma_f32_16x16x32_bf16 v[16:19], v[230:233], v[206:209], v[16:19]
	v_mfma_f32_16x16x32_bf16 v[4:7], v[222:225], v[214:217], v[4:7]
	v_mfma_f32_16x16x32_bf16 v[0:3], v[230:233], v[214:217], v[0:3]
	v_mfma_f32_16x16x32_bf16 v[52:55], v[226:229], v[194:197], v[52:55]
	v_mfma_f32_16x16x32_bf16 v[48:51], v[234:237], v[194:197], v[48:51]
	v_mfma_f32_16x16x32_bf16 v[36:39], v[226:229], v[202:205], v[36:39]
	v_mfma_f32_16x16x32_bf16 v[32:35], v[234:237], v[202:205], v[32:35]
	v_mfma_f32_16x16x32_bf16 v[20:23], v[226:229], v[210:213], v[20:23]
	v_mfma_f32_16x16x32_bf16 v[16:19], v[234:237], v[210:213], v[16:19]
	v_mfma_f32_16x16x32_bf16 v[4:7], v[226:229], v[218:221], v[4:7]
	v_mfma_f32_16x16x32_bf16 v[0:3], v[234:237], v[218:221], v[0:3]
	s_setprio 0
	s_add_i32 s75, 0, 0x18000
	v_add_u32_e32 v128, s75, v146
	s_barrier
	ds_read_b128 v[140:143], v128
	ds_read_b128 v[178:181], v128 offset:1024
	ds_read_b128 v[182:185], v128 offset:2048
	ds_read_b128 v[186:189], v128 offset:3072
	s_add_u32 s16, s16, 0x40000
	s_addc_u32 s17, s17, 0
	s_mov_b32 m0, s77
	v_lshl_add_u64 v[222:223], s[16:17], 0, v[132:133]
	ds_read_b128 v[190:193], v148 offset:32768
	ds_read_b128 v[194:197], v148 offset:33792
	ds_read_b128 v[198:201], v148 offset:34816
	ds_read_b128 v[202:205], v148 offset:35840
	ds_read_b128 v[206:209], v148 offset:36864
	ds_read_b128 v[210:213], v148 offset:37888
	ds_read_b128 v[214:217], v148 offset:38912
	ds_read_b128 v[218:221], v148 offset:39936
	global_load_lds_dwordx4 v[222:223], off
	s_mov_b32 m0, s58
	v_lshl_add_u64 v[222:223], s[16:17], 0, v[134:135]
	global_load_lds_dwordx4 v[222:223], off
	s_waitcnt lgkmcnt(8)
	s_setprio 1
	s_barrier
	s_waitcnt lgkmcnt(0)
	v_mfma_f32_16x16x32_bf16 v[124:127], v[140:143], v[190:193], v[124:127]
	v_mfma_f32_16x16x32_bf16 v[120:123], v[182:185], v[190:193], v[120:123]
	v_mfma_f32_16x16x32_bf16 v[108:111], v[140:143], v[198:201], v[108:111]
	v_mfma_f32_16x16x32_bf16 v[104:107], v[182:185], v[198:201], v[104:107]
	v_mfma_f32_16x16x32_bf16 v[92:95], v[140:143], v[206:209], v[92:95]
	v_mfma_f32_16x16x32_bf16 v[88:91], v[182:185], v[206:209], v[88:91]
	v_mfma_f32_16x16x32_bf16 v[76:79], v[140:143], v[214:217], v[76:79]
	v_mfma_f32_16x16x32_bf16 v[72:75], v[182:185], v[214:217], v[72:75]
	v_mfma_f32_16x16x32_bf16 v[124:127], v[178:181], v[194:197], v[124:127]
	v_mfma_f32_16x16x32_bf16 v[120:123], v[186:189], v[194:197], v[120:123]
	v_mfma_f32_16x16x32_bf16 v[108:111], v[178:181], v[202:205], v[108:111]
	v_mfma_f32_16x16x32_bf16 v[104:107], v[186:189], v[202:205], v[104:107]
	v_mfma_f32_16x16x32_bf16 v[92:95], v[178:181], v[210:213], v[92:95]
	v_mfma_f32_16x16x32_bf16 v[88:91], v[186:189], v[210:213], v[88:91]
	v_mfma_f32_16x16x32_bf16 v[76:79], v[178:181], v[218:221], v[76:79]
	v_mfma_f32_16x16x32_bf16 v[72:75], v[186:189], v[218:221], v[72:75]
	s_setprio 0
	s_barrier
	s_add_i32 s16, 0, 0x1c000
	s_add_i32 s17, s75, s65
	v_add_u32_e32 v128, s16, v146
	v_lshl_add_u64 v[144:145], v[144:145], 0, s[88:89]
	s_mov_b32 m0, s17
	ds_read_b128 v[222:225], v128
	ds_read_b128 v[226:229], v128 offset:1024
	ds_read_b128 v[230:233], v128 offset:2048
	ds_read_b128 v[234:237], v128 offset:3072
	global_load_lds_dwordx4 v[144:145], off
	s_add_i32 m0, s17, 0x2000
	v_lshl_add_u64 v[144:145], v[150:151], 0, s[88:89]
	global_load_lds_dwordx4 v[144:145], off
	s_setprio 1
	s_barrier
	s_waitcnt lgkmcnt(0)
	v_mfma_f32_16x16x32_bf16 v[116:119], v[222:225], v[190:193], v[116:119]
	v_mfma_f32_16x16x32_bf16 v[112:115], v[230:233], v[190:193], v[112:115]
	v_mfma_f32_16x16x32_bf16 v[100:103], v[222:225], v[198:201], v[100:103]
	v_mfma_f32_16x16x32_bf16 v[96:99], v[230:233], v[198:201], v[96:99]
	v_mfma_f32_16x16x32_bf16 v[84:87], v[222:225], v[206:209], v[84:87]
	v_mfma_f32_16x16x32_bf16 v[80:83], v[230:233], v[206:209], v[80:83]
	v_mfma_f32_16x16x32_bf16 v[68:71], v[222:225], v[214:217], v[68:71]
	v_mfma_f32_16x16x32_bf16 v[64:67], v[230:233], v[214:217], v[64:67]
	v_mfma_f32_16x16x32_bf16 v[116:119], v[226:229], v[194:197], v[116:119]
	v_mfma_f32_16x16x32_bf16 v[112:115], v[234:237], v[194:197], v[112:115]
	v_mfma_f32_16x16x32_bf16 v[100:103], v[226:229], v[202:205], v[100:103]
	v_mfma_f32_16x16x32_bf16 v[96:99], v[234:237], v[202:205], v[96:99]
	v_mfma_f32_16x16x32_bf16 v[84:87], v[226:229], v[210:213], v[84:87]
	v_mfma_f32_16x16x32_bf16 v[80:83], v[234:237], v[210:213], v[80:83]
	v_mfma_f32_16x16x32_bf16 v[68:71], v[226:229], v[218:221], v[68:71]
	v_mfma_f32_16x16x32_bf16 v[64:67], v[234:237], v[218:221], v[64:67]
	s_setprio 0
	s_mov_b32 m0, s82
	v_lshl_add_u64 v[144:145], v[162:163], 0, s[88:89]
	s_barrier
; DI unsigned pk2(float a, float b) { f32x2 v = {a, b}; nbf2 r = __builtin_convertvector(v, nbf2); return __builtin_bit_cast(unsigned, r); }
; #define PG8_STAGE(bufoff, gbase, voff) do { _Pragma("unroll") for (int _i = 0; _i < 2; ++_i) \
;         __builtin_amdgcn_global_load_lds((const unsigned*)((const char*)(gbase) + (voff)[_i]), (LAS unsigned*)(lds + (bufoff) + ldsw + _i * 8192), 16, 0, 0); } while (0)
; #define PG8_LDA(dst, b, h) do { _Pragma("unroll") for (int m = 0; m < 4; ++m) _Pragma("unroll") for (int k = 0; k < 2; ++k) dst[m][k] = *(const LAS bf16x8*)(lds + PG8_SA(b, h) + aoff + m * 2048 + k * 1024); } while (0)
; template <class Epi, class Sched>
; DI void gemm_phase(LAS unsigned char* lds, const Gemm g, const Sched& S, const Epi& E) {
;     ...
;             PG8_LDA(At, 1, 1); PG8_STAGE(PG8_SA(1, 0), a3, voffA);
;             PG8_BAR; PG8_WAIT_L(0); PG8_MMA(1, 0, At, B0); PG8_BAR; PG8_SCHED;
;             PG8_STAGE(PG8_SB(1, 1), b3 + hstep, voffB);
;             PG8_WAIT_V(6); PG8_BAR; PG8_MMA(1, 1, At, B1); PG8_BAR;
;         }
;         E(acc, cur, wr, wc, fr, fq);
;     DI void operator()(const f32x4 (&acc)[2][2][4][2], const pg8::Unit& u, int wr, int wc, int fr, int fq) const {
;         const int row0 = u.pm * 256 + wr * 64 + fr, colL = wc * 32 + 8 * fq;
;         const bool special = ((u.pm & 7) == 7 || u.pm == 64) && (u.pn < 6 || u.pn >= 8);
; #pragma unroll
;         for (int ai = 0; ai < 2; ++ai)
; #pragma unroll
;             for (int m = 0; m < 4; ++m) { const int r = row0 + ai * 128 + m * 16;
; #pragma unroll
;                 for (int bj = 0; bj < 2; ++bj) { const int pc = u.pn * 256 + bj * 128 + colL; const f32x4 v0 = acc[ai][bj][m][0], v1 = acc[ai][bj][m][1];
;                     u32x4 w; w.x = pk2(v0[0], v0[1]); w.y = pk2(v0[2], v0[3]); w.z = pk2(v1[0], v1[1]); w.w = pk2(v1[2], v1[3]);
;                     *(u32x4*)(P + (size_t)r * NPROJ + pc) = w;
;                     if (special) { float* dst = nullptr;
;                         if (r < NPROMPT) { const int tpos = r & 2047, b = r >> 11;
;                             if (pc < QKVD) { if (tpos >= 2045) dst = out + OUT_CP + ((size_t)(layer * 8 + b) * 3 + (tpos - 2045)) * QKVD + pc; }
;                             else if (pc >= 2048) { if (tpos >= 2033) dst = out + OUT_PP + ((size_t)(layer * 8 + b) * 15 + (tpos - 2033)) * 512 + (pc - 2048); } }
	ds_read_b128 v[190:193], v148 offset:49152
	ds_read_b128 v[194:197], v148 offset:50176
	ds_read_b128 v[198:201], v148 offset:51200
	ds_read_b128 v[202:205], v148 offset:52224
	ds_read_b128 v[206:209], v148 offset:53248
	ds_read_b128 v[210:213], v148 offset:54272
	ds_read_b128 v[214:217], v148 offset:55296
	ds_read_b128 v[218:221], v148 offset:56320
	global_load_lds_dwordx4 v[144:145], off
	s_mov_b32 m0, s83
	v_lshl_add_u64 v[144:145], v[238:239], 0, s[88:89]
	global_load_lds_dwordx4 v[144:145], off
	s_setprio 1
	s_barrier
	s_waitcnt lgkmcnt(0)
	v_mfma_f32_16x16x32_bf16 v[60:63], v[140:143], v[190:193], v[60:63]
	v_mfma_f32_16x16x32_bf16 v[56:59], v[182:185], v[190:193], v[56:59]
	v_mfma_f32_16x16x32_bf16 v[44:47], v[140:143], v[198:201], v[44:47]
	v_mfma_f32_16x16x32_bf16 v[40:43], v[182:185], v[198:201], v[40:43]
	v_mfma_f32_16x16x32_bf16 v[28:31], v[140:143], v[206:209], v[28:31]
	v_mfma_f32_16x16x32_bf16 v[24:27], v[182:185], v[206:209], v[24:27]
	v_mfma_f32_16x16x32_bf16 v[12:15], v[140:143], v[214:217], v[12:15]
	v_mfma_f32_16x16x32_bf16 v[8:11], v[182:185], v[214:217], v[8:11]
	v_mfma_f32_16x16x32_bf16 v[60:63], v[178:181], v[194:197], v[60:63]
	v_mfma_f32_16x16x32_bf16 v[56:59], v[186:189], v[194:197], v[56:59]
	v_mfma_f32_16x16x32_bf16 v[44:47], v[178:181], v[202:205], v[44:47]
	v_mfma_f32_16x16x32_bf16 v[40:43], v[186:189], v[202:205], v[40:43]
	v_mfma_f32_16x16x32_bf16 v[28:31], v[178:181], v[210:213], v[28:31]
	v_mfma_f32_16x16x32_bf16 v[24:27], v[186:189], v[210:213], v[24:27]
	v_mfma_f32_16x16x32_bf16 v[12:15], v[178:181], v[218:221], v[12:15]
	v_mfma_f32_16x16x32_bf16 v[8:11], v[186:189], v[218:221], v[8:11]
	s_setprio 0
	s_barrier
	s_add_u32 s14, s14, 0x40080
	s_addc_u32 s15, s15, 0
	s_add_i32 s16, s16, s65
	s_mov_b32 m0, s16
	v_lshl_add_u64 v[140:141], s[14:15], 0, v[132:133]
	global_load_lds_dwordx4 v[140:141], off
	s_add_i32 m0, s16, 0x2000
	v_lshl_add_u64 v[140:141], s[14:15], 0, v[134:135]
	global_load_lds_dwordx4 v[140:141], off
	s_waitcnt vmcnt(6)
	s_setprio 1
	s_barrier
	v_mfma_f32_16x16x32_bf16 v[52:55], v[222:225], v[190:193], v[52:55]
	v_mfma_f32_16x16x32_bf16 v[48:51], v[230:233], v[190:193], v[48:51]
	v_mfma_f32_16x16x32_bf16 v[36:39], v[222:225], v[198:201], v[36:39]
	v_mfma_f32_16x16x32_bf16 v[32:35], v[230:233], v[198:201], v[32:35]
	v_mfma_f32_16x16x32_bf16 v[20:23], v[222:225], v[206:209], v[20:23]
	v_mfma_f32_16x16x32_bf16 v[16:19], v[230:233], v[206:209], v[16:19]
	v_mfma_f32_16x16x32_bf16 v[4:7], v[222:225], v[214:217], v[4:7]
	v_mfma_f32_16x16x32_bf16 v[0:3], v[230:233], v[214:217], v[0:3]
	v_mfma_f32_16x16x32_bf16 v[52:55], v[226:229], v[194:197], v[52:55]
	v_mfma_f32_16x16x32_bf16 v[48:51], v[234:237], v[194:197], v[48:51]
	v_mfma_f32_16x16x32_bf16 v[36:39], v[226:229], v[202:205], v[36:39]
	v_mfma_f32_16x16x32_bf16 v[32:35], v[234:237], v[202:205], v[32:35]
	v_mfma_f32_16x16x32_bf16 v[20:23], v[226:229], v[210:213], v[20:23]
	v_mfma_f32_16x16x32_bf16 v[16:19], v[234:237], v[210:213], v[16:19]
	v_mfma_f32_16x16x32_bf16 v[4:7], v[226:229], v[218:221], v[4:7]
	v_mfma_f32_16x16x32_bf16 v[0:3], v[234:237], v[218:221], v[0:3]
	s_setprio 0
	s_add_i32 s41, s41, 2
	s_add_u32 s8, s8, 0x100
	s_addc_u32 s9, s9, 0
	s_add_u32 s39, s39, 0x100
	s_addc_u32 s40, s40, 0
	s_cmp_gt_u32 s41, 13
	s_barrier
	s_cbranch_scc0 .LBB0_503
	s_lshl_b32 s75, s12, 8
	s_add_i32 s75, s75, s91
	s_and_b32 s8, s12, 7
	s_cmp_eq_u32 s8, 7
	s_cselect_b64 s[8:9], -1, 0
	s_cmp_eq_u32 s12, 64
	s_cselect_b64 s[12:13], -1, 0
	s_or_b64 s[8:9], s[12:13], s[8:9]
	s_add_i32 s11, s10, -8
	s_cmp_lt_u32 s11, -2
	s_cselect_b64 s[12:13], -1, 0
	s_lshl_b32 s35, s10, 8
	v_or_b32_e32 v149, s75, v131
	s_and_b64 s[14:15], s[8:9], s[12:13]
	v_or_b32_e32 v140, s35, v147
	v_mov_b64_e32 v[142:143], s[72:73]
	s_cmpk_gt_u32 s75, 0x407f
	v_mad_i64_i32 v[142:143], s[8:9], v149, s42, v[142:143]
	v_ashrrev_i32_e32 v141, 31, v140
	v_cndmask_b32_e64 v144, 0, 1, s[14:15]
	v_cmp_gt_i32_e64 s[10:11], s45, v149
	s_cselect_b64 s[12:13], -1, 0
	v_add_u32_e32 v128, 0xffffc000, v149
	v_cvt_pk_bf16_f32 v178, v124, v125
	v_cvt_pk_bf16_f32 v179, v126, v127
	v_cvt_pk_bf16_f32 v180, v120, v121
	v_cvt_pk_bf16_f32 v181, v122, v123
	v_lshl_add_u64 v[142:143], v[140:141], 1, v[142:143]
	v_cmp_ne_u32_e64 s[8:9], 1, v144
	s_andn2_b64 vcc, exec, s[14:15]
	global_store_dwordx4 v[142:143], v[178:181], off
	s_cbranch_vccnz .LBB0_515
	s_nor_b64 s[16:17], s[12:13], s[10:11]
	v_mov_b64_e32 v[144:145], 0
	s_and_saveexec_b64 s[14:15], s[16:17]
	s_cbranch_execz .LBB0_512
	v_cmp_lt_i32_e32 vcc, s55, v140
	s_and_saveexec_b64 s[16:17], vcc
	s_xor_b64 s[16:17], exec, s[16:17]
	s_cbranch_execz .LBB0_509
	s_cmpk_lt_u32 s35, 0x800
	v_mov_b64_e32 v[144:145], 0
	s_cbranch_scc1 .LBB0_509
	v_add_u32_e32 v150, s78, v128
	v_mov_b64_e32 v[144:145], s[20:21]
	s_movk_i32 s38, 0x7800
	v_mad_i64_i32 v[144:145], s[38:39], v150, s38, v[144:145]
	v_lshl_add_u64 v[144:145], v[140:141], 2, v[144:145]
	s_mov_b64 s[38:39], 0xd305000
	v_lshl_add_u64 v[144:145], v[144:145], 0, s[38:39]

; #define PG8_STAGE(bufoff, gbase, voff) do { _Pragma("unroll") for (int _i = 0; _i < 2; ++_i) \
;         __builtin_amdgcn_global_load_lds((const unsigned*)((const char*)(gbase) + (voff)[_i]), (LAS unsigned*)(lds + (bufoff) + ldsw + _i * 8192), 16, 0, 0); } while (0)
; #define PG8_LDA(dst, b, h) do { _Pragma("unroll") for (int m = 0; m < 4; ++m) _Pragma("unroll") for (int k = 0; k < 2; ++k) dst[m][k] = *(const LAS bf16x8*)(lds + PG8_SA(b, h) + aoff + m * 2048 + k * 1024); } while (0)
; #define PG8_LDB(dst, b, h) do { _Pragma("unroll") for (int n = 0; n < 2; ++n) _Pragma("unroll") for (int k = 0; k < 2; ++k) dst[n][k] = *(const LAS bf16x8*)(lds + PG8_SB(b, h) + boff + n * 2048 + k * 1024); } while (0)
; #define PG8_MMA(ai, bj, At, Bt) do { __builtin_amdgcn_s_setprio(1); _Pragma("unroll") for (int m = 0; m < 4; ++m) _Pragma("unroll") for (int n = 0; n < 2; ++n) _Pragma("unroll") for (int k = 0; k < 2; ++k) \
;         acc[ai][bj][m][n] = __builtin_amdgcn_mfma_f32_16x16x32_bf16(Bt[n][k], At[m][k], acc[ai][bj][m][n], 0, 0, 0); __builtin_amdgcn_s_setprio(0); } while (0)
; #define PG8_WAIT_V(n) asm volatile("s_waitcnt vmcnt(" #n ")" ::: "memory")
; #define PG8_WAIT_L(n) asm volatile("s_waitcnt lgkmcnt(" #n ")" ::: "memory")
; #define PG8_BAR __builtin_amdgcn_s_barrier()
; #define PG8_SCHED __builtin_amdgcn_sched_barrier(0)
; template <class Epi, class Sched>
; DI void gemm_phase(LAS unsigned char* lds, const Gemm g, const Sched& S, const Epi& E) {
;     ...
;             PG8_LDB(B0, 0, 0); PG8_SCHED; PG8_LDA(At, 0, 0); PG8_STAGE(PG8_SA(1, 1), a1 + hstep, voffA);
;             PG8_WAIT_L(8); PG8_BAR; PG8_WAIT_L(0); PG8_MMA(0, 0, At, B0); PG8_BAR; PG8_SCHED;
;             PG8_LDB(B1, 0, 1); PG8_STAGE(PG8_SB(0, 0), b2, voffB);
;             PG8_BAR; PG8_WAIT_L(0); PG8_MMA(0, 1, At, B1); PG8_BAR;
;             PG8_LDA(At, 0, 1); PG8_STAGE(PG8_SA(0, 0), a2, voffA);
;             PG8_BAR; PG8_WAIT_L(0); PG8_MMA(1, 0, At, B0); PG8_BAR; PG8_SCHED;
;             PG8_STAGE(PG8_SB(0, 1), b2 + hstep, voffB);
;             PG8_WAIT_V(6); PG8_BAR; PG8_MMA(1, 1, At, B1); PG8_BAR;
.LBB0_800:
	s_add_u32 s34, s18, s28
	s_addc_u32 s35, s19, s29
	s_add_u32 s34, s34, 0x100
	s_addc_u32 s35, s35, 0
	s_add_u32 s36, s13, s28
	s_addc_u32 s37, s95, s29
	s_add_i32 s92, 0, 0x10000
	v_add_u32_e32 v150, s92, v131
	ds_read_b128 v[180:183], v150
	ds_read_b128 v[184:187], v150 offset:1024
	ds_read_b128 v[188:191], v150 offset:2048
	ds_read_b128 v[192:195], v150 offset:3072
	s_cmp_eq_u32 s17, vcc_lo
	s_cselect_b32 s35, s15, s35
	s_cselect_b32 s34, s14, s34
	s_cselect_b32 s37, s9, s37
	s_cselect_b32 s36, s8, s36
	v_lshl_add_u64 v[150:151], v[146:147], 0, s[28:29]
	s_add_i32 m0, s67, 0xc000
	ds_read_b128 v[196:199], v178
	ds_read_b128 v[200:203], v178 offset:1024
	ds_read_b128 v[204:207], v178 offset:2048
	ds_read_b128 v[208:211], v178 offset:3072
	ds_read_b128 v[212:215], v178 offset:4096
	ds_read_b128 v[216:219], v178 offset:5120
	ds_read_b128 v[220:223], v178 offset:6144
	ds_read_b128 v[224:227], v178 offset:7168
	global_load_lds_dwordx4 v[150:151], off
	s_add_i32 m0, s67, 0xe000
	v_lshl_add_u64 v[150:151], v[148:149], 0, s[28:29]
	global_load_lds_dwordx4 v[150:151], off
	s_waitcnt lgkmcnt(8)
	s_setprio 1
	s_barrier
	s_waitcnt lgkmcnt(0)
	v_mfma_f32_16x16x32_bf16 v[124:127], v[180:183], v[196:199], v[124:127]
	v_mfma_f32_16x16x32_bf16 v[120:123], v[188:191], v[196:199], v[120:123]
	v_mfma_f32_16x16x32_bf16 v[112:115], v[180:183], v[204:207], v[112:115]
	v_mfma_f32_16x16x32_bf16 v[104:107], v[188:191], v[204:207], v[104:107]
	v_mfma_f32_16x16x32_bf16 v[96:99], v[180:183], v[212:215], v[96:99]
	v_mfma_f32_16x16x32_bf16 v[88:91], v[188:191], v[212:215], v[88:91]
	v_mfma_f32_16x16x32_bf16 v[80:83], v[180:183], v[220:223], v[80:83]
	v_mfma_f32_16x16x32_bf16 v[72:75], v[188:191], v[220:223], v[72:75]
	v_mfma_f32_16x16x32_bf16 v[124:127], v[184:187], v[200:203], v[124:127]
	v_mfma_f32_16x16x32_bf16 v[120:123], v[192:195], v[200:203], v[120:123]
	v_mfma_f32_16x16x32_bf16 v[112:115], v[184:187], v[208:211], v[112:115]
	v_mfma_f32_16x16x32_bf16 v[104:107], v[192:195], v[208:211], v[104:107]
	v_mfma_f32_16x16x32_bf16 v[96:99], v[184:187], v[216:219], v[96:99]
	v_mfma_f32_16x16x32_bf16 v[88:91], v[192:195], v[216:219], v[88:91]
	v_mfma_f32_16x16x32_bf16 v[80:83], v[184:187], v[224:227], v[80:83]
	v_mfma_f32_16x16x32_bf16 v[72:75], v[192:195], v[224:227], v[72:75]
	s_setprio 0
	s_barrier
	s_add_i32 s93, 0, 0x14000
	v_add_u32_e32 v150, s93, v131
	s_add_i32 s92, s92, s66
	ds_read_b128 v[228:231], v150
	ds_read_b128 v[232:235], v150 offset:1024
	ds_read_b128 v[236:239], v150 offset:2048
	ds_read_b128 v[240:243], v150 offset:3072
	v_lshl_add_u64 v[150:151], s[36:37], 0, v[128:129]
	s_mov_b32 m0, s92
	v_lshl_add_u64 v[244:245], s[36:37], 0, v[132:133]
	global_load_lds_dwordx4 v[150:151], off
	s_add_i32 m0, s92, 0x2000
	s_nop 0
	global_load_lds_dwordx4 v[244:245], off
	s_setprio 1
	s_barrier
	s_waitcnt lgkmcnt(0)
	v_mfma_f32_16x16x32_bf16 v[116:119], v[228:231], v[196:199], v[116:119]
	v_mfma_f32_16x16x32_bf16 v[108:111], v[236:239], v[196:199], v[108:111]
	v_mfma_f32_16x16x32_bf16 v[100:103], v[228:231], v[204:207], v[100:103]
	v_mfma_f32_16x16x32_bf16 v[92:95], v[236:239], v[204:207], v[92:95]
	v_mfma_f32_16x16x32_bf16 v[84:87], v[228:231], v[212:215], v[84:87]
	v_mfma_f32_16x16x32_bf16 v[76:79], v[236:239], v[212:215], v[76:79]
	v_mfma_f32_16x16x32_bf16 v[68:71], v[228:231], v[220:223], v[68:71]
	v_mfma_f32_16x16x32_bf16 v[64:67], v[236:239], v[220:223], v[64:67]
	v_mfma_f32_16x16x32_bf16 v[116:119], v[232:235], v[200:203], v[116:119]
	v_mfma_f32_16x16x32_bf16 v[108:111], v[240:243], v[200:203], v[108:111]
	v_mfma_f32_16x16x32_bf16 v[100:103], v[232:235], v[208:211], v[100:103]
	v_mfma_f32_16x16x32_bf16 v[92:95], v[240:243], v[208:211], v[92:95]
	v_mfma_f32_16x16x32_bf16 v[84:87], v[232:235], v[216:219], v[84:87]
	v_mfma_f32_16x16x32_bf16 v[76:79], v[240:243], v[216:219], v[76:79]
	v_mfma_f32_16x16x32_bf16 v[68:71], v[232:235], v[224:227], v[68:71]
	v_mfma_f32_16x16x32_bf16 v[64:67], v[240:243], v[224:227], v[64:67]
	s_setprio 0
	s_mov_b32 m0, s67
	v_lshl_add_u64 v[246:247], s[34:35], 0, v[128:129]
	s_barrier
	ds_read_b128 v[196:199], v178 offset:16384
	ds_read_b128 v[200:203], v178 offset:17408
	ds_read_b128 v[204:207], v178 offset:18432
	ds_read_b128 v[208:211], v178 offset:19456
	ds_read_b128 v[212:215], v178 offset:20480
	ds_read_b128 v[216:219], v178 offset:21504
	ds_read_b128 v[220:223], v178 offset:22528
	ds_read_b128 v[224:227], v178 offset:23552
	global_load_lds_dwordx4 v[246:247], off
	s_mov_b32 m0, s77
	v_lshl_add_u64 v[248:249], s[34:35], 0, v[132:133]
	global_load_lds_dwordx4 v[248:249], off
	s_setprio 1
	s_barrier
	s_waitcnt lgkmcnt(0)
	v_mfma_f32_16x16x32_bf16 v[60:63], v[180:183], v[196:199], v[60:63]
	v_mfma_f32_16x16x32_bf16 v[56:59], v[188:191], v[196:199], v[56:59]
	v_mfma_f32_16x16x32_bf16 v[48:51], v[180:183], v[204:207], v[48:51]
	v_mfma_f32_16x16x32_bf16 v[40:43], v[188:191], v[204:207], v[40:43]
	v_mfma_f32_16x16x32_bf16 v[32:35], v[180:183], v[212:215], v[32:35]
	v_mfma_f32_16x16x32_bf16 v[24:27], v[188:191], v[212:215], v[24:27]
	v_mfma_f32_16x16x32_bf16 v[16:19], v[180:183], v[220:223], v[16:19]
	v_mfma_f32_16x16x32_bf16 v[8:11], v[188:191], v[220:223], v[8:11]
	v_mfma_f32_16x16x32_bf16 v[60:63], v[184:187], v[200:203], v[60:63]
	v_mfma_f32_16x16x32_bf16 v[56:59], v[192:195], v[200:203], v[56:59]
	v_mfma_f32_16x16x32_bf16 v[48:51], v[184:187], v[208:211], v[48:51]
	v_mfma_f32_16x16x32_bf16 v[40:43], v[192:195], v[208:211], v[40:43]
	v_mfma_f32_16x16x32_bf16 v[32:35], v[184:187], v[216:219], v[32:35]
	v_mfma_f32_16x16x32_bf16 v[24:27], v[192:195], v[216:219], v[24:27]
	v_mfma_f32_16x16x32_bf16 v[16:19], v[184:187], v[224:227], v[16:19]
	v_mfma_f32_16x16x32_bf16 v[8:11], v[192:195], v[224:227], v[8:11]
	s_setprio 0
	s_barrier
; #define PG8_STAGE(bufoff, gbase, voff) do { _Pragma("unroll") for (int _i = 0; _i < 2; ++_i) \
;         __builtin_amdgcn_global_load_lds((const unsigned*)((const char*)(gbase) + (voff)[_i]), (LAS unsigned*)(lds + (bufoff) + ldsw + _i * 8192), 16, 0, 0); } while (0)
; #define PG8_LDA(dst, b, h) do { _Pragma("unroll") for (int m = 0; m < 4; ++m) _Pragma("unroll") for (int k = 0; k < 2; ++k) dst[m][k] = *(const LAS bf16x8*)(lds + PG8_SA(b, h) + aoff + m * 2048 + k * 1024); } while (0)
; #define PG8_LDB(dst, b, h) do { _Pragma("unroll") for (int n = 0; n < 2; ++n) _Pragma("unroll") for (int k = 0; k < 2; ++k) dst[n][k] = *(const LAS bf16x8*)(lds + PG8_SB(b, h) + boff + n * 2048 + k * 1024); } while (0)
; #define PG8_MMA(ai, bj, At, Bt) do { __builtin_amdgcn_s_setprio(1); _Pragma("unroll") for (int m = 0; m < 4; ++m) _Pragma("unroll") for (int n = 0; n < 2; ++n) _Pragma("unroll") for (int k = 0; k < 2; ++k) \
;         acc[ai][bj][m][n] = __builtin_amdgcn_mfma_f32_16x16x32_bf16(Bt[n][k], At[m][k], acc[ai][bj][m][n], 0, 0, 0); __builtin_amdgcn_s_setprio(0); } while (0)
; #define PG8_WAIT_V(n) asm volatile("s_waitcnt vmcnt(" #n ")" ::: "memory")
; #define PG8_WAIT_L(n) asm volatile("s_waitcnt lgkmcnt(" #n ")" ::: "memory")
; #define PG8_BAR __builtin_amdgcn_s_barrier()
; #define PG8_SCHED __builtin_amdgcn_sched_barrier(0)
; template <class Epi, class Sched>
; DI void gemm_phase(LAS unsigned char* lds, const Gemm g, const Sched& S, const Epi& E) {
;     ...
;             PG8_STAGE(PG8_SB(0, 1), b2 + hstep, voffB);
;             PG8_WAIT_V(6); PG8_BAR; PG8_MMA(1, 1, At, B1); PG8_BAR;
;             PG8_LDB(B0, 1, 0); PG8_SCHED; PG8_LDA(At, 1, 0); PG8_STAGE(PG8_SA(0, 1), a2 + hstep, voffA);
;             PG8_WAIT_L(8); PG8_BAR; PG8_WAIT_L(0); PG8_MMA(0, 0, At, B0); PG8_BAR; PG8_SCHED;
;             PG8_LDB(B1, 1, 1); PG8_STAGE(PG8_SB(1, 0), b3, voffB);
;             PG8_BAR; PG8_WAIT_L(0); PG8_MMA(0, 1, At, B1); PG8_BAR;
;             PG8_LDA(At, 1, 1); PG8_STAGE(PG8_SA(1, 0), a3, voffA);
;             PG8_BAR; PG8_WAIT_L(0); PG8_MMA(1, 0, At, B0); PG8_BAR; PG8_SCHED;
;             PG8_STAGE(PG8_SB(1, 1), b3 + hstep, voffB);
;             PG8_WAIT_V(6); PG8_BAR; PG8_MMA(1, 1, At, B1); PG8_BAR;
	s_add_u32 s36, s36, s2
	s_addc_u32 s37, s37, 0
	s_add_i32 s92, s93, s66
	v_lshl_add_u64 v[250:251], s[36:37], 0, v[128:129]
	s_mov_b32 m0, s92
	v_lshl_add_u64 v[162:163], s[36:37], 0, v[132:133]
	global_load_lds_dwordx4 v[250:251], off
	s_add_i32 m0, s92, 0x2000
	s_nop 0
	global_load_lds_dwordx4 v[162:163], off
	s_waitcnt vmcnt(6)
	s_setprio 1
	s_barrier
	v_mfma_f32_16x16x32_bf16 v[52:55], v[228:231], v[196:199], v[52:55]
	v_mfma_f32_16x16x32_bf16 v[44:47], v[236:239], v[196:199], v[44:47]
	v_mfma_f32_16x16x32_bf16 v[36:39], v[228:231], v[204:207], v[36:39]
	v_mfma_f32_16x16x32_bf16 v[28:31], v[236:239], v[204:207], v[28:31]
	v_mfma_f32_16x16x32_bf16 v[20:23], v[228:231], v[212:215], v[20:23]
	v_mfma_f32_16x16x32_bf16 v[12:15], v[236:239], v[212:215], v[12:15]
	v_mfma_f32_16x16x32_bf16 v[4:7], v[228:231], v[220:223], v[4:7]
	v_mfma_f32_16x16x32_bf16 v[0:3], v[236:239], v[220:223], v[0:3]
	v_mfma_f32_16x16x32_bf16 v[52:55], v[232:235], v[200:203], v[52:55]
	v_mfma_f32_16x16x32_bf16 v[44:47], v[240:243], v[200:203], v[44:47]
	v_mfma_f32_16x16x32_bf16 v[36:39], v[232:235], v[208:211], v[36:39]
	v_mfma_f32_16x16x32_bf16 v[28:31], v[240:243], v[208:211], v[28:31]
	v_mfma_f32_16x16x32_bf16 v[20:23], v[232:235], v[216:219], v[20:23]
	v_mfma_f32_16x16x32_bf16 v[12:15], v[240:243], v[216:219], v[12:15]
	v_mfma_f32_16x16x32_bf16 v[4:7], v[232:235], v[224:227], v[4:7]
	v_mfma_f32_16x16x32_bf16 v[0:3], v[240:243], v[224:227], v[0:3]
	s_setprio 0
	s_add_i32 s36, 0, 0x18000
	v_add_u32_e32 v192, s36, v131
	s_barrier
	ds_read_b128 v[180:183], v192
	ds_read_b128 v[184:187], v192 offset:1024
	ds_read_b128 v[188:191], v192 offset:2048
	ds_read_b128 v[192:195], v192 offset:3072
	s_add_u32 s34, s34, s2
	s_addc_u32 s35, s35, 0
	s_mov_b32 m0, s78
	v_lshl_add_u64 v[228:229], s[34:35], 0, v[128:129]
	ds_read_b128 v[196:199], v178 offset:32768
	ds_read_b128 v[200:203], v178 offset:33792
	ds_read_b128 v[204:207], v178 offset:34816
	ds_read_b128 v[208:211], v178 offset:35840
	ds_read_b128 v[212:215], v178 offset:36864
	ds_read_b128 v[216:219], v178 offset:37888
	ds_read_b128 v[220:223], v178 offset:38912
	ds_read_b128 v[224:227], v178 offset:39936
	global_load_lds_dwordx4 v[228:229], off
	s_mov_b32 m0, s79
	v_lshl_add_u64 v[228:229], s[34:35], 0, v[132:133]
	global_load_lds_dwordx4 v[228:229], off
	s_waitcnt lgkmcnt(8)
	s_setprio 1
	s_barrier
	s_waitcnt lgkmcnt(0)
	v_mfma_f32_16x16x32_bf16 v[124:127], v[180:183], v[196:199], v[124:127]
	v_mfma_f32_16x16x32_bf16 v[120:123], v[188:191], v[196:199], v[120:123]
	v_mfma_f32_16x16x32_bf16 v[112:115], v[180:183], v[204:207], v[112:115]
	v_mfma_f32_16x16x32_bf16 v[104:107], v[188:191], v[204:207], v[104:107]
	v_mfma_f32_16x16x32_bf16 v[96:99], v[180:183], v[212:215], v[96:99]
	v_mfma_f32_16x16x32_bf16 v[88:91], v[188:191], v[212:215], v[88:91]
	v_mfma_f32_16x16x32_bf16 v[80:83], v[180:183], v[220:223], v[80:83]
	v_mfma_f32_16x16x32_bf16 v[72:75], v[188:191], v[220:223], v[72:75]
	v_mfma_f32_16x16x32_bf16 v[124:127], v[184:187], v[200:203], v[124:127]
	v_mfma_f32_16x16x32_bf16 v[120:123], v[192:195], v[200:203], v[120:123]
	v_mfma_f32_16x16x32_bf16 v[112:115], v[184:187], v[208:211], v[112:115]
	v_mfma_f32_16x16x32_bf16 v[104:107], v[192:195], v[208:211], v[104:107]
	v_mfma_f32_16x16x32_bf16 v[96:99], v[184:187], v[216:219], v[96:99]
	v_mfma_f32_16x16x32_bf16 v[88:91], v[192:195], v[216:219], v[88:91]
	v_mfma_f32_16x16x32_bf16 v[80:83], v[184:187], v[224:227], v[80:83]
	v_mfma_f32_16x16x32_bf16 v[72:75], v[192:195], v[224:227], v[72:75]
	s_setprio 0
	s_barrier
	s_add_i32 s34, 0, 0x1c000
	s_add_i32 s35, s36, s66
	v_add_u32_e32 v240, s34, v131
	v_lshl_add_u64 v[150:151], v[150:151], 0, s[88:89]
	s_mov_b32 m0, s35
	ds_read_b128 v[228:231], v240
	ds_read_b128 v[232:235], v240 offset:1024
	ds_read_b128 v[236:239], v240 offset:2048
	ds_read_b128 v[240:243], v240 offset:3072
	global_load_lds_dwordx4 v[150:151], off
	s_add_i32 m0, s35, 0x2000
	v_lshl_add_u64 v[150:151], v[244:245], 0, s[88:89]
	global_load_lds_dwordx4 v[150:151], off
	s_setprio 1
	s_barrier
	s_waitcnt lgkmcnt(0)
	v_mfma_f32_16x16x32_bf16 v[116:119], v[228:231], v[196:199], v[116:119]
	v_mfma_f32_16x16x32_bf16 v[108:111], v[236:239], v[196:199], v[108:111]
	v_mfma_f32_16x16x32_bf16 v[100:103], v[228:231], v[204:207], v[100:103]
	v_mfma_f32_16x16x32_bf16 v[92:95], v[236:239], v[204:207], v[92:95]
	v_mfma_f32_16x16x32_bf16 v[84:87], v[228:231], v[212:215], v[84:87]
	v_mfma_f32_16x16x32_bf16 v[76:79], v[236:239], v[212:215], v[76:79]
	v_mfma_f32_16x16x32_bf16 v[68:71], v[228:231], v[220:223], v[68:71]
	v_mfma_f32_16x16x32_bf16 v[64:67], v[236:239], v[220:223], v[64:67]
	v_mfma_f32_16x16x32_bf16 v[116:119], v[232:235], v[200:203], v[116:119]
	v_mfma_f32_16x16x32_bf16 v[108:111], v[240:243], v[200:203], v[108:111]
	v_mfma_f32_16x16x32_bf16 v[100:103], v[232:235], v[208:211], v[100:103]
	v_mfma_f32_16x16x32_bf16 v[92:95], v[240:243], v[208:211], v[92:95]
	v_mfma_f32_16x16x32_bf16 v[84:87], v[232:235], v[216:219], v[84:87]
	v_mfma_f32_16x16x32_bf16 v[76:79], v[240:243], v[216:219], v[76:79]
	v_mfma_f32_16x16x32_bf16 v[68:71], v[232:235], v[224:227], v[68:71]
	v_mfma_f32_16x16x32_bf16 v[64:67], v[240:243], v[224:227], v[64:67]
	s_setprio 0
	s_mov_b32 m0, s80
	v_lshl_add_u64 v[150:151], v[246:247], 0, s[88:89]
	s_barrier
	ds_read_b128 v[196:199], v178 offset:49152
	ds_read_b128 v[200:203], v178 offset:50176
	ds_read_b128 v[204:207], v178 offset:51200
	ds_read_b128 v[208:211], v178 offset:52224
	ds_read_b128 v[212:215], v178 offset:53248
	ds_read_b128 v[216:219], v178 offset:54272
	ds_read_b128 v[220:223], v178 offset:55296
	ds_read_b128 v[224:227], v178 offset:56320
	global_load_lds_dwordx4 v[150:151], off
	s_mov_b32 m0, s81
	v_lshl_add_u64 v[150:151], v[248:249], 0, s[88:89]
	global_load_lds_dwordx4 v[150:151], off
	s_setprio 1
	s_barrier
; #define PG8_STAGE(bufoff, gbase, voff) do { _Pragma("unroll") for (int _i = 0; _i < 2; ++_i) \
;         __builtin_amdgcn_global_load_lds((const unsigned*)((const char*)(gbase) + (voff)[_i]), (LAS unsigned*)(lds + (bufoff) + ldsw + _i * 8192), 16, 0, 0); } while (0)
; #define PG8_LDA(dst, b, h) do { _Pragma("unroll") for (int m = 0; m < 4; ++m) _Pragma("unroll") for (int k = 0; k < 2; ++k) dst[m][k] = *(const LAS bf16x8*)(lds + PG8_SA(b, h) + aoff + m * 2048 + k * 1024); } while (0)
; #define PG8_MMA(ai, bj, At, Bt) do { __builtin_amdgcn_s_setprio(1); _Pragma("unroll") for (int m = 0; m < 4; ++m) _Pragma("unroll") for (int n = 0; n < 2; ++n) _Pragma("unroll") for (int k = 0; k < 2; ++k) \
;         acc[ai][bj][m][n] = __builtin_amdgcn_mfma_f32_16x16x32_bf16(Bt[n][k], At[m][k], acc[ai][bj][m][n], 0, 0, 0); __builtin_amdgcn_s_setprio(0); } while (0)
; #define PG8_WAIT_V(n) asm volatile("s_waitcnt vmcnt(" #n ")" ::: "memory")
; #define PG8_WAIT_L(n) asm volatile("s_waitcnt lgkmcnt(" #n ")" ::: "memory")
; #define PG8_BAR __builtin_amdgcn_s_barrier()
; #define PG8_SCHED __builtin_amdgcn_sched_barrier(0)
; template <class Epi, class Sched>
; DI void gemm_phase(LAS unsigned char* lds, const Gemm g, const Sched& S, const Epi& E) {
;     ...
;             PG8_LDA(At, 1, 1); PG8_STAGE(PG8_SA(1, 0), a3, voffA);
;             PG8_BAR; PG8_WAIT_L(0); PG8_MMA(1, 0, At, B0); PG8_BAR; PG8_SCHED;
;             PG8_STAGE(PG8_SB(1, 1), b3 + hstep, voffB);
;             PG8_WAIT_V(6); PG8_BAR; PG8_MMA(1, 1, At, B1); PG8_BAR;
;         }
;         E(acc, cur, wr, wc, fr, fq);
	s_waitcnt lgkmcnt(0)
	v_mfma_f32_16x16x32_bf16 v[60:63], v[180:183], v[196:199], v[60:63]
	v_mfma_f32_16x16x32_bf16 v[56:59], v[188:191], v[196:199], v[56:59]
	v_mfma_f32_16x16x32_bf16 v[48:51], v[180:183], v[204:207], v[48:51]
	v_mfma_f32_16x16x32_bf16 v[40:43], v[188:191], v[204:207], v[40:43]
	v_mfma_f32_16x16x32_bf16 v[32:35], v[180:183], v[212:215], v[32:35]
	v_mfma_f32_16x16x32_bf16 v[24:27], v[188:191], v[212:215], v[24:27]
	v_mfma_f32_16x16x32_bf16 v[16:19], v[180:183], v[220:223], v[16:19]
	v_mfma_f32_16x16x32_bf16 v[8:11], v[188:191], v[220:223], v[8:11]
	v_mfma_f32_16x16x32_bf16 v[60:63], v[184:187], v[200:203], v[60:63]
	v_mfma_f32_16x16x32_bf16 v[56:59], v[192:195], v[200:203], v[56:59]
	v_mfma_f32_16x16x32_bf16 v[48:51], v[184:187], v[208:211], v[48:51]
	v_mfma_f32_16x16x32_bf16 v[40:43], v[192:195], v[208:211], v[40:43]
	v_mfma_f32_16x16x32_bf16 v[32:35], v[184:187], v[216:219], v[32:35]
	v_mfma_f32_16x16x32_bf16 v[24:27], v[192:195], v[216:219], v[24:27]
	v_mfma_f32_16x16x32_bf16 v[16:19], v[184:187], v[224:227], v[16:19]
	v_mfma_f32_16x16x32_bf16 v[8:11], v[192:195], v[224:227], v[8:11]
	s_setprio 0
	s_barrier
	s_add_i32 s34, s34, s66
	s_mov_b32 m0, s34
	v_lshl_add_u64 v[150:151], v[250:251], 0, s[88:89]
	global_load_lds_dwordx4 v[150:151], off
	s_add_i32 m0, s34, 0x2000
	v_lshl_add_u64 v[150:151], v[162:163], 0, s[88:89]
	global_load_lds_dwordx4 v[150:151], off
	s_waitcnt vmcnt(6)
	s_setprio 1
	s_barrier
	v_mfma_f32_16x16x32_bf16 v[52:55], v[228:231], v[196:199], v[52:55]
	v_mfma_f32_16x16x32_bf16 v[44:47], v[236:239], v[196:199], v[44:47]
	v_mfma_f32_16x16x32_bf16 v[36:39], v[228:231], v[204:207], v[36:39]
	v_mfma_f32_16x16x32_bf16 v[28:31], v[236:239], v[204:207], v[28:31]
	v_mfma_f32_16x16x32_bf16 v[20:23], v[228:231], v[212:215], v[20:23]
	v_mfma_f32_16x16x32_bf16 v[12:15], v[236:239], v[212:215], v[12:15]
	v_mfma_f32_16x16x32_bf16 v[4:7], v[228:231], v[220:223], v[4:7]
	v_mfma_f32_16x16x32_bf16 v[0:3], v[236:239], v[220:223], v[0:3]
	v_mfma_f32_16x16x32_bf16 v[52:55], v[232:235], v[200:203], v[52:55]
	v_mfma_f32_16x16x32_bf16 v[44:47], v[240:243], v[200:203], v[44:47]
	v_mfma_f32_16x16x32_bf16 v[36:39], v[232:235], v[208:211], v[36:39]
	v_mfma_f32_16x16x32_bf16 v[28:31], v[240:243], v[208:211], v[28:31]
	v_mfma_f32_16x16x32_bf16 v[20:23], v[232:235], v[216:219], v[20:23]
	v_mfma_f32_16x16x32_bf16 v[12:15], v[240:243], v[216:219], v[12:15]
	v_mfma_f32_16x16x32_bf16 v[4:7], v[232:235], v[224:227], v[4:7]
	v_mfma_f32_16x16x32_bf16 v[0:3], v[240:243], v[224:227], v[0:3]
	s_setprio 0
	s_add_i32 s34, vcc_lo, 2
	s_add_u32 s28, s28, 0x100
	s_addc_u32 s29, s29, 0
	s_cmp_ge_i32 vcc_lo, s17
	s_mov_b32 vcc_lo, s34
	s_barrier
	s_cbranch_scc0 .LBB0_800
	v_lshl_or_b32 v146, s94, 8, v137
	v_cmp_ne_u32_e32 vcc, 0, v135
	v_ashrrev_i32_e32 v147, 31, v146
	s_cbranch_vccz .LBB0_803
;     DI void operator()(const f32x4 (&acc)[2][2][4][2], const pg8::Unit& u, int wr, int wc, int fr, int fq) const {
;     ...
;         if (u.split) {
;             float* P0 = PART + ((size_t)(u.kt0 / u.nt) * 256 + (wr * 64 + fr)) * DM + col0;
; #pragma unroll
;             for (int ai = 0; ai < 2; ++ai)
; #pragma unroll
;                 for (int m = 0; m < 4; ++m) { float* rowp = P0 + (size_t)(ai * 128 + m * 16) * DM;
; #pragma unroll
;                     for (int bj = 0; bj < 2; ++bj)
; #pragma unroll
;                         for (int n = 0; n < 2; ++n) *(f32x4*)(rowp + bj * 128 + n * 16) = acc[ai][bj][m][n] * scale; }
;             return; }
	s_abs_i32 s13, s17
	v_cvt_f32_u32_e32 v135, s13
	s_sub_i32 s18, 0, s13
	s_xor_b32 s17, s16, s17
	s_abs_i32 s16, s16
	v_rcp_iflag_f32_e32 v148, v135
	s_ashr_i32 s17, s17, 31
	v_mov_b32_e32 v135, v134
	v_pk_mul_f32 v[180:181], v[140:141], v[124:125]
	v_mul_f32_e32 v148, 0x4f7ffffe, v148
	v_cvt_u32_f32_e32 v148, v148
	v_pk_mul_f32 v[182:183], v[134:135], v[126:127]
	v_readfirstlane_b32 s19, v148
	s_mul_i32 s18, s18, s19
	s_mul_hi_u32 s18, s19, s18
	s_add_i32 s19, s19, s18
	s_mul_hi_u32 s18, s16, s19
	s_mul_i32 s19, s18, s13
	s_sub_i32 s16, s16, s19
	s_add_i32 s28, s18, 1
	s_sub_i32 s19, s16, s13
	s_cmp_ge_u32 s16, s13
	s_cselect_b32 s18, s28, s18
	s_cselect_b32 s16, s19, s16
	s_add_i32 s19, s18, 1
	s_cmp_ge_u32 s16, s13
	s_cselect_b32 s13, s19, s18
	s_xor_b32 s13, s13, s17
	s_sub_i32 s16, s13, s17
	s_ashr_i32 s17, s16, 31
	s_lshl_b64 s[16:17], s[16:17], 20
	v_lshl_add_u64 v[148:149], v[138:139], 0, s[16:17]
	v_lshl_add_u64 v[148:149], v[146:147], 2, v[148:149]
	global_store_dwordx4 v[148:149], v[180:183], off
	v_add_co_u32_e32 v150, vcc, s44, v148
	s_nop 0
	v_pk_mul_f32 v[182:183], v[134:135], v[122:123]
	v_pk_mul_f32 v[180:181], v[140:141], v[120:121]
	global_store_dwordx4 v[148:149], v[180:183], off offset:64
	v_addc_co_u32_e32 v151, vcc, 0, v149, vcc
	s_nop 0
	v_pk_mul_f32 v[182:183], v[134:135], v[118:119]
	v_pk_mul_f32 v[180:181], v[140:141], v[116:117]
	global_store_dwordx4 v[148:149], v[180:183], off offset:512
	s_mov_b32 s13, 0x20000
	s_nop 0
	v_pk_mul_f32 v[182:183], v[134:135], v[110:111]
	v_pk_mul_f32 v[180:181], v[140:141], v[108:109]
	global_store_dwordx4 v[148:149], v[180:183], off offset:576
	s_nop 1
	v_pk_mul_f32 v[182:183], v[134:135], v[114:115]
	v_pk_mul_f32 v[180:181], v[140:141], v[112:113]
	global_store_dwordx4 v[150:151], v[180:183], off
	s_nop 1
	v_pk_mul_f32 v[182:183], v[134:135], v[106:107]
	v_pk_mul_f32 v[180:181], v[140:141], v[104:105]
	global_store_dwordx4 v[150:151], v[180:183], off offset:64
	s_nop 1
	v_pk_mul_f32 v[182:183], v[134:135], v[102:103]
	v_pk_mul_f32 v[180:181], v[140:141], v[100:101]
	global_store_dwordx4 v[150:151], v[180:183], off offset:512
	s_nop 1
	v_pk_mul_f32 v[182:183], v[134:135], v[94:95]
	v_pk_mul_f32 v[180:181], v[140:141], v[92:93]
	global_store_dwordx4 v[150:151], v[180:183], off offset:576
	v_add_co_u32_e32 v150, vcc, s13, v148
	s_nop 0
	v_pk_mul_f32 v[182:183], v[134:135], v[98:99]
	v_pk_mul_f32 v[180:181], v[140:141], v[96:97]
	v_addc_co_u32_e32 v151, vcc, 0, v149, vcc
	global_store_dwordx4 v[150:151], v[180:183], off
	s_mov_b32 s13, 0x30000
	s_nop 0
	v_pk_mul_f32 v[182:183], v[134:135], v[90:91]
	v_pk_mul_f32 v[180:181], v[140:141], v[88:89]
	global_store_dwordx4 v[150:151], v[180:183], off offset:64
	s_nop 1
	v_pk_mul_f32 v[182:183], v[134:135], v[86:87]
	v_pk_mul_f32 v[180:181], v[140:141], v[84:85]
	global_store_dwordx4 v[150:151], v[180:183], off offset:512
	s_nop 1
	v_pk_mul_f32 v[182:183], v[134:135], v[78:79]
	v_pk_mul_f32 v[180:181], v[140:141], v[76:77]
	global_store_dwordx4 v[150:151], v[180:183], off offset:576
	v_add_co_u32_e32 v150, vcc, s13, v148
	s_nop 0
	v_pk_mul_f32 v[182:183], v[134:135], v[82:83]
	v_pk_mul_f32 v[180:181], v[140:141], v[80:81]
	v_addc_co_u32_e32 v151, vcc, 0, v149, vcc
	global_store_dwordx4 v[150:151], v[180:183], off
	s_mov_b32 s13, 0x80000
	s_nop 0
	v_pk_mul_f32 v[182:183], v[134:135], v[74:75]
	v_pk_mul_f32 v[180:181], v[140:141], v[72:73]
	global_store_dwordx4 v[150:151], v[180:183], off offset:64
	s_nop 1
	v_pk_mul_f32 v[182:183], v[134:135], v[70:71]
	v_pk_mul_f32 v[180:181], v[140:141], v[68:69]
	global_store_dwordx4 v[150:151], v[180:183], off offset:512
	s_nop 1
	v_pk_mul_f32 v[182:183], v[134:135], v[66:67]
	v_pk_mul_f32 v[180:181], v[140:141], v[64:65]
	global_store_dwordx4 v[150:151], v[180:183], off offset:576
	v_add_co_u32_e32 v150, vcc, s13, v148
	s_nop 0
	v_pk_mul_f32 v[182:183], v[134:135], v[62:63]
	v_pk_mul_f32 v[180:181], v[140:141], v[60:61]
	v_addc_co_u32_e32 v151, vcc, 0, v149, vcc
	global_store_dwordx4 v[150:151], v[180:183], off
	s_mov_b32 s13, 0x90000
	s_nop 0
	v_pk_mul_f32 v[182:183], v[134:135], v[58:59]
	v_pk_mul_f32 v[180:181], v[140:141], v[56:57]
	global_store_dwordx4 v[150:151], v[180:183], off offset:64
	s_nop 1
	v_pk_mul_f32 v[182:183], v[134:135], v[54:55]
	v_pk_mul_f32 v[180:181], v[140:141], v[52:53]
	global_store_dwordx4 v[150:151], v[180:183], off offset:512
	s_nop 1
	v_pk_mul_f32 v[182:183], v[134:135], v[46:47]
	v_pk_mul_f32 v[180:181], v[140:141], v[44:45]
	global_store_dwordx4 v[150:151], v[180:183], off offset:576
	v_add_co_u32_e32 v150, vcc, s13, v148
	s_nop 0
	v_pk_mul_f32 v[182:183], v[134:135], v[50:51]
	v_pk_mul_f32 v[180:181], v[140:141], v[48:49]
	v_addc_co_u32_e32 v151, vcc, 0, v149, vcc
	global_store_dwordx4 v[150:151], v[180:183], off
	s_mov_b32 s13, 0xa0000
	s_nop 0
	v_pk_mul_f32 v[182:183], v[134:135], v[42:43]
	v_pk_mul_f32 v[180:181], v[140:141], v[40:41]
	global_store_dwordx4 v[150:151], v[180:183], off offset:64
	s_nop 1
	v_pk_mul_f32 v[182:183], v[134:135], v[38:39]
	v_pk_mul_f32 v[180:181], v[140:141], v[36:37]
	global_store_dwordx4 v[150:151], v[180:183], off offset:512
	s_nop 1
	v_pk_mul_f32 v[182:183], v[134:135], v[30:31]
	v_pk_mul_f32 v[180:181], v[140:141], v[28:29]
	global_store_dwordx4 v[150:151], v[180:183], off offset:576
	v_add_co_u32_e32 v150, vcc, s13, v148
	s_nop 0
	v_pk_mul_f32 v[182:183], v[134:135], v[34:35]
	v_pk_mul_f32 v[180:181], v[140:141], v[32:33]
	v_addc_co_u32_e32 v151, vcc, 0, v149, vcc
	global_store_dwordx4 v[150:151], v[180:183], off
	s_mov_b32 s13, 0xb0000
	v_add_co_u32_e32 v184, vcc, s13, v148
	v_pk_mul_f32 v[182:183], v[134:135], v[26:27]
	v_pk_mul_f32 v[180:181], v[140:141], v[24:25]
	global_store_dwordx4 v[150:151], v[180:183], off offset:64
	v_addc_co_u32_e32 v185, vcc, 0, v149, vcc
	s_nop 0
	v_pk_mul_f32 v[182:183], v[134:135], v[22:23]
	v_pk_mul_f32 v[180:181], v[140:141], v[20:21]
	global_store_dwordx4 v[150:151], v[180:183], off offset:512
	v_pk_mul_f32 v[148:149], v[140:141], v[8:9]
	s_nop 0
	v_pk_mul_f32 v[182:183], v[134:135], v[14:15]
	v_pk_mul_f32 v[180:181], v[140:141], v[12:13]
	global_store_dwordx4 v[150:151], v[180:183], off offset:576
	v_pk_mul_f32 v[150:151], v[134:135], v[10:11]
	global_store_dwordx4 v[184:185], v[148:151], off offset:64
	v_pk_mul_f32 v[182:183], v[134:135], v[18:19]
	v_pk_mul_f32 v[180:181], v[140:141], v[16:17]
	v_pk_mul_f32 v[150:151], v[134:135], v[6:7]
	v_pk_mul_f32 v[148:149], v[140:141], v[4:5]
	global_store_dwordx4 v[184:185], v[148:151], off offset:512
	global_store_dwordx4 v[184:185], v[180:183], off
	s_nop 0
	v_pk_mul_f32 v[150:151], v[134:135], v[2:3]
	v_pk_mul_f32 v[148:149], v[140:141], v[0:1]
	global_store_dwordx4 v[184:185], v[148:151], off offset:576
	s_mov_b32 s92, s54
	s_movk_i32 s93, 0x2000
	s_cbranch_execnz .LBB0_788
	s_branch .LBB0_804

; #define PG8_STAGE(bufoff, gbase, voff) do { _Pragma("unroll") for (int _i = 0; _i < 2; ++_i) \
;         __builtin_amdgcn_global_load_lds((const unsigned*)((const char*)(gbase) + (voff)[_i]), (LAS unsigned*)(lds + (bufoff) + ldsw + _i * 8192), 16, 0, 0); } while (0)
; #define PG8_LDA(dst, b, h) do { _Pragma("unroll") for (int m = 0; m < 4; ++m) _Pragma("unroll") for (int k = 0; k < 2; ++k) dst[m][k] = *(const LAS bf16x8*)(lds + PG8_SA(b, h) + aoff + m * 2048 + k * 1024); } while (0)
; #define PG8_LDB(dst, b, h) do { _Pragma("unroll") for (int n = 0; n < 2; ++n) _Pragma("unroll") for (int k = 0; k < 2; ++k) dst[n][k] = *(const LAS bf16x8*)(lds + PG8_SB(b, h) + boff + n * 2048 + k * 1024); } while (0)
; #define PG8_MMA(ai, bj, At, Bt) do { __builtin_amdgcn_s_setprio(1); _Pragma("unroll") for (int m = 0; m < 4; ++m) _Pragma("unroll") for (int n = 0; n < 2; ++n) _Pragma("unroll") for (int k = 0; k < 2; ++k) \
;         acc[ai][bj][m][n] = __builtin_amdgcn_mfma_f32_16x16x32_bf16(Bt[n][k], At[m][k], acc[ai][bj][m][n], 0, 0, 0); __builtin_amdgcn_s_setprio(0); } while (0)
; #define PG8_WAIT_V(n) asm volatile("s_waitcnt vmcnt(" #n ")" ::: "memory")
; #define PG8_WAIT_L(n) asm volatile("s_waitcnt lgkmcnt(" #n ")" ::: "memory")
; #define PG8_BAR __builtin_amdgcn_s_barrier()
; template <class Epi, class Sched>
; DI void gemm_phase(LAS unsigned char* lds, const Gemm g, const Sched& S, const Epi& E) {
;     ...
;         for (int t = 0; t < nt; t += 2) {
;             const bool last = (t == nt - 2);
;             const char* a1 = cA + (size_t)(t + 1) * kstep;
;             const char* a2 = last ? nA : cA + (size_t)(t + 2) * kstep; const char* b2 = last ? nB : cB + (size_t)(t + 2) * kstep;
;             const char* a3 = a2 + kstep; const char* b3 = b2 + kstep;
;             PG8_LDB(B0, 0, 0); PG8_SCHED; PG8_LDA(At, 0, 0); PG8_STAGE(PG8_SA(1, 1), a1 + hstep, voffA);
;             PG8_WAIT_L(8); PG8_BAR; PG8_WAIT_L(0); PG8_MMA(0, 0, At, B0); PG8_BAR; PG8_SCHED;
;             PG8_LDB(B1, 0, 1); PG8_STAGE(PG8_SB(0, 0), b2, voffB);
;             PG8_BAR; PG8_WAIT_L(0); PG8_MMA(0, 1, At, B1); PG8_BAR;
;             PG8_LDA(At, 0, 1); PG8_STAGE(PG8_SA(0, 0), a2, voffA);
;             PG8_BAR; PG8_WAIT_L(0); PG8_MMA(1, 0, At, B0); PG8_BAR; PG8_SCHED;
;             PG8_STAGE(PG8_SB(0, 1), b2 + hstep, voffB);
;             PG8_WAIT_V(6); PG8_BAR; PG8_MMA(1, 1, At, B1); PG8_BAR;
.LBB0_822:
	s_add_u32 s28, s18, 0xfffc0080
	s_addc_u32 s29, s19, -1
	s_add_i32 s78, 0, 0x10000
	v_add_u32_e32 v138, s78, v140
	ds_read_b128 v[144:147], v138
	ds_read_b128 v[148:151], v138 offset:1024
	ds_read_b128 v[178:181], v138 offset:2048
	ds_read_b128 v[182:185], v138 offset:3072
	s_cmp_eq_u32 s77, 12
	s_cselect_b32 s35, s13, s29
	s_cselect_b32 s34, s66, s28
	s_cselect_b32 s29, s11, s75
	s_cselect_b32 s28, s67, s74
	v_lshl_add_u64 v[138:139], s[18:19], 0, v[134:135]
	s_add_i32 m0, s37, 0xc000
	ds_read_b128 v[186:189], v142
	ds_read_b128 v[190:193], v142 offset:1024
	ds_read_b128 v[194:197], v142 offset:2048
	ds_read_b128 v[198:201], v142 offset:3072
	ds_read_b128 v[202:205], v142 offset:4096
	ds_read_b128 v[206:209], v142 offset:5120
	ds_read_b128 v[210:213], v142 offset:6144
	ds_read_b128 v[214:217], v142 offset:7168
	global_load_lds_dwordx4 v[138:139], off
	s_add_i32 m0, s37, 0xe000
	v_lshl_add_u64 v[138:139], s[18:19], 0, v[136:137]
	global_load_lds_dwordx4 v[138:139], off
	s_waitcnt lgkmcnt(8)
	s_setprio 1
	s_barrier
	s_waitcnt lgkmcnt(0)
	v_mfma_f32_16x16x32_bf16 v[120:123], v[144:147], v[186:189], v[120:123]
	v_mfma_f32_16x16x32_bf16 v[124:127], v[178:181], v[186:189], v[124:127]
	v_mfma_f32_16x16x32_bf16 v[104:107], v[144:147], v[194:197], v[104:107]
	v_mfma_f32_16x16x32_bf16 v[108:111], v[178:181], v[194:197], v[108:111]
	v_mfma_f32_16x16x32_bf16 v[88:91], v[144:147], v[202:205], v[88:91]
	v_mfma_f32_16x16x32_bf16 v[92:95], v[178:181], v[202:205], v[92:95]
	v_mfma_f32_16x16x32_bf16 v[72:75], v[144:147], v[210:213], v[72:75]
	v_mfma_f32_16x16x32_bf16 v[76:79], v[178:181], v[210:213], v[76:79]
	v_mfma_f32_16x16x32_bf16 v[120:123], v[148:151], v[190:193], v[120:123]
	v_mfma_f32_16x16x32_bf16 v[124:127], v[182:185], v[190:193], v[124:127]
	v_mfma_f32_16x16x32_bf16 v[104:107], v[148:151], v[198:201], v[104:107]
	v_mfma_f32_16x16x32_bf16 v[108:111], v[182:185], v[198:201], v[108:111]
	v_mfma_f32_16x16x32_bf16 v[88:91], v[148:151], v[206:209], v[88:91]
	v_mfma_f32_16x16x32_bf16 v[92:95], v[182:185], v[206:209], v[92:95]
	v_mfma_f32_16x16x32_bf16 v[72:75], v[148:151], v[214:217], v[72:75]
	v_mfma_f32_16x16x32_bf16 v[76:79], v[182:185], v[214:217], v[76:79]
	s_setprio 0
	s_barrier
	s_add_i32 s80, 0, 0x14000
	v_add_u32_e32 v138, s80, v140
	s_add_i32 s78, s78, s36
	ds_read_b128 v[218:221], v138
	ds_read_b128 v[222:225], v138 offset:1024
	ds_read_b128 v[226:229], v138 offset:2048
	ds_read_b128 v[230:233], v138 offset:3072
	v_lshl_add_u64 v[138:139], s[28:29], 0, v[128:129]
	s_mov_b32 m0, s78
	v_lshl_add_u64 v[234:235], s[28:29], 0, v[132:133]
	global_load_lds_dwordx4 v[138:139], off
	s_add_i32 m0, s78, 0x2000
	s_nop 0
	global_load_lds_dwordx4 v[234:235], off
	s_setprio 1
	s_barrier
	s_waitcnt lgkmcnt(0)
	v_mfma_f32_16x16x32_bf16 v[112:115], v[218:221], v[186:189], v[112:115]
	v_mfma_f32_16x16x32_bf16 v[116:119], v[226:229], v[186:189], v[116:119]
	v_mfma_f32_16x16x32_bf16 v[96:99], v[218:221], v[194:197], v[96:99]
	v_mfma_f32_16x16x32_bf16 v[100:103], v[226:229], v[194:197], v[100:103]
	v_mfma_f32_16x16x32_bf16 v[80:83], v[218:221], v[202:205], v[80:83]
	v_mfma_f32_16x16x32_bf16 v[84:87], v[226:229], v[202:205], v[84:87]
	v_mfma_f32_16x16x32_bf16 v[64:67], v[218:221], v[210:213], v[64:67]
	v_mfma_f32_16x16x32_bf16 v[68:71], v[226:229], v[210:213], v[68:71]
	v_mfma_f32_16x16x32_bf16 v[112:115], v[222:225], v[190:193], v[112:115]
	v_mfma_f32_16x16x32_bf16 v[116:119], v[230:233], v[190:193], v[116:119]
	v_mfma_f32_16x16x32_bf16 v[96:99], v[222:225], v[198:201], v[96:99]
	v_mfma_f32_16x16x32_bf16 v[100:103], v[230:233], v[198:201], v[100:103]
	v_mfma_f32_16x16x32_bf16 v[80:83], v[222:225], v[206:209], v[80:83]
	v_mfma_f32_16x16x32_bf16 v[84:87], v[230:233], v[206:209], v[84:87]
	v_mfma_f32_16x16x32_bf16 v[64:67], v[222:225], v[214:217], v[64:67]
	v_mfma_f32_16x16x32_bf16 v[68:71], v[230:233], v[214:217], v[68:71]
	s_setprio 0
	s_mov_b32 m0, s37
	v_lshl_add_u64 v[236:237], s[34:35], 0, v[128:129]
	s_barrier
	ds_read_b128 v[186:189], v142 offset:16384
	ds_read_b128 v[190:193], v142 offset:17408
	ds_read_b128 v[194:197], v142 offset:18432
	ds_read_b128 v[198:201], v142 offset:19456
	ds_read_b128 v[202:205], v142 offset:20480
	ds_read_b128 v[206:209], v142 offset:21504
	ds_read_b128 v[210:213], v142 offset:22528
	ds_read_b128 v[214:217], v142 offset:23552
	global_load_lds_dwordx4 v[236:237], off
	s_mov_b32 m0, s38
	v_lshl_add_u64 v[238:239], s[34:35], 0, v[132:133]
	global_load_lds_dwordx4 v[238:239], off
	s_setprio 1
	s_barrier
	s_waitcnt lgkmcnt(0)
	v_mfma_f32_16x16x32_bf16 v[56:59], v[144:147], v[186:189], v[56:59]
	v_mfma_f32_16x16x32_bf16 v[60:63], v[178:181], v[186:189], v[60:63]
	v_mfma_f32_16x16x32_bf16 v[40:43], v[144:147], v[194:197], v[40:43]
	v_mfma_f32_16x16x32_bf16 v[44:47], v[178:181], v[194:197], v[44:47]
	v_mfma_f32_16x16x32_bf16 v[24:27], v[144:147], v[202:205], v[24:27]
	v_mfma_f32_16x16x32_bf16 v[28:31], v[178:181], v[202:205], v[28:31]
	v_mfma_f32_16x16x32_bf16 v[8:11], v[144:147], v[210:213], v[8:11]
	v_mfma_f32_16x16x32_bf16 v[12:15], v[178:181], v[210:213], v[12:15]
	v_mfma_f32_16x16x32_bf16 v[56:59], v[148:151], v[190:193], v[56:59]
	v_mfma_f32_16x16x32_bf16 v[60:63], v[182:185], v[190:193], v[60:63]
	v_mfma_f32_16x16x32_bf16 v[40:43], v[148:151], v[198:201], v[40:43]
	v_mfma_f32_16x16x32_bf16 v[44:47], v[182:185], v[198:201], v[44:47]
	v_mfma_f32_16x16x32_bf16 v[24:27], v[148:151], v[206:209], v[24:27]
	v_mfma_f32_16x16x32_bf16 v[28:31], v[182:185], v[206:209], v[28:31]
	v_mfma_f32_16x16x32_bf16 v[8:11], v[148:151], v[214:217], v[8:11]
	v_mfma_f32_16x16x32_bf16 v[12:15], v[182:185], v[214:217], v[12:15]
	s_setprio 0
	s_barrier
; #define PG8_STAGE(bufoff, gbase, voff) do { _Pragma("unroll") for (int _i = 0; _i < 2; ++_i) \
;         __builtin_amdgcn_global_load_lds((const unsigned*)((const char*)(gbase) + (voff)[_i]), (LAS unsigned*)(lds + (bufoff) + ldsw + _i * 8192), 16, 0, 0); } while (0)
; #define PG8_LDA(dst, b, h) do { _Pragma("unroll") for (int m = 0; m < 4; ++m) _Pragma("unroll") for (int k = 0; k < 2; ++k) dst[m][k] = *(const LAS bf16x8*)(lds + PG8_SA(b, h) + aoff + m * 2048 + k * 1024); } while (0)
; #define PG8_LDB(dst, b, h) do { _Pragma("unroll") for (int n = 0; n < 2; ++n) _Pragma("unroll") for (int k = 0; k < 2; ++k) dst[n][k] = *(const LAS bf16x8*)(lds + PG8_SB(b, h) + boff + n * 2048 + k * 1024); } while (0)
; #define PG8_MMA(ai, bj, At, Bt) do { __builtin_amdgcn_s_setprio(1); _Pragma("unroll") for (int m = 0; m < 4; ++m) _Pragma("unroll") for (int n = 0; n < 2; ++n) _Pragma("unroll") for (int k = 0; k < 2; ++k) \
;         acc[ai][bj][m][n] = __builtin_amdgcn_mfma_f32_16x16x32_bf16(Bt[n][k], At[m][k], acc[ai][bj][m][n], 0, 0, 0); __builtin_amdgcn_s_setprio(0); } while (0)
; #define PG8_WAIT_V(n) asm volatile("s_waitcnt vmcnt(" #n ")" ::: "memory")
; #define PG8_WAIT_L(n) asm volatile("s_waitcnt lgkmcnt(" #n ")" ::: "memory")
; #define PG8_BAR __builtin_amdgcn_s_barrier()
; #define PG8_SCHED __builtin_amdgcn_sched_barrier(0)
; template <class Epi, class Sched>
; DI void gemm_phase(LAS unsigned char* lds, const Gemm g, const Sched& S, const Epi& E) {
;     ...
;             PG8_STAGE(PG8_SB(0, 1), b2 + hstep, voffB);
;             PG8_WAIT_V(6); PG8_BAR; PG8_MMA(1, 1, At, B1); PG8_BAR;
;             PG8_LDB(B0, 1, 0); PG8_SCHED; PG8_LDA(At, 1, 0); PG8_STAGE(PG8_SA(0, 1), a2 + hstep, voffA);
;             PG8_WAIT_L(8); PG8_BAR; PG8_WAIT_L(0); PG8_MMA(0, 0, At, B0); PG8_BAR; PG8_SCHED;
;             PG8_LDB(B1, 1, 1); PG8_STAGE(PG8_SB(1, 0), b3, voffB);
;             PG8_BAR; PG8_WAIT_L(0); PG8_MMA(0, 1, At, B1); PG8_BAR;
;             PG8_LDA(At, 1, 1); PG8_STAGE(PG8_SA(1, 0), a3, voffA);
;             PG8_BAR; PG8_WAIT_L(0); PG8_MMA(1, 0, At, B0); PG8_BAR; PG8_SCHED;
;             PG8_STAGE(PG8_SB(1, 1), b3 + hstep, voffB);
;             PG8_WAIT_V(6); PG8_BAR; PG8_MMA(1, 1, At, B1); PG8_BAR;
	s_add_u32 s78, s28, 0x40000
	s_addc_u32 s79, s29, 0
	s_add_i32 s80, s80, s36
	s_mov_b32 m0, s80
	v_lshl_add_u64 v[144:145], s[78:79], 0, v[128:129]
	global_load_lds_dwordx4 v[144:145], off
	s_add_i32 m0, s80, 0x2000
	v_lshl_add_u64 v[144:145], s[78:79], 0, v[132:133]
	global_load_lds_dwordx4 v[144:145], off
	s_waitcnt vmcnt(6)
	s_setprio 1
	s_barrier
	v_mfma_f32_16x16x32_bf16 v[48:51], v[218:221], v[186:189], v[48:51]
	v_mfma_f32_16x16x32_bf16 v[52:55], v[226:229], v[186:189], v[52:55]
	v_mfma_f32_16x16x32_bf16 v[32:35], v[218:221], v[194:197], v[32:35]
	v_mfma_f32_16x16x32_bf16 v[36:39], v[226:229], v[194:197], v[36:39]
	v_mfma_f32_16x16x32_bf16 v[16:19], v[218:221], v[202:205], v[16:19]
	v_mfma_f32_16x16x32_bf16 v[20:23], v[226:229], v[202:205], v[20:23]
	v_mfma_f32_16x16x32_bf16 v[0:3], v[218:221], v[210:213], v[0:3]
	v_mfma_f32_16x16x32_bf16 v[4:7], v[226:229], v[210:213], v[4:7]
	v_mfma_f32_16x16x32_bf16 v[48:51], v[222:225], v[190:193], v[48:51]
	v_mfma_f32_16x16x32_bf16 v[52:55], v[230:233], v[190:193], v[52:55]
	v_mfma_f32_16x16x32_bf16 v[32:35], v[222:225], v[198:201], v[32:35]
	v_mfma_f32_16x16x32_bf16 v[36:39], v[230:233], v[198:201], v[36:39]
	v_mfma_f32_16x16x32_bf16 v[16:19], v[222:225], v[206:209], v[16:19]
	v_mfma_f32_16x16x32_bf16 v[20:23], v[230:233], v[206:209], v[20:23]
	v_mfma_f32_16x16x32_bf16 v[0:3], v[222:225], v[214:217], v[0:3]
	v_mfma_f32_16x16x32_bf16 v[4:7], v[230:233], v[214:217], v[4:7]
	s_setprio 0
	s_add_i32 s78, 0, 0x18000
	v_add_u32_e32 v143, s78, v140
	s_barrier
	ds_read_b128 v[144:147], v143
	ds_read_b128 v[148:151], v143 offset:1024
	ds_read_b128 v[178:181], v143 offset:2048
	ds_read_b128 v[182:185], v143 offset:3072
	s_add_u32 s34, s34, 0x40000
	s_addc_u32 s35, s35, 0
	s_mov_b32 m0, s39
	v_lshl_add_u64 v[218:219], s[34:35], 0, v[128:129]
	ds_read_b128 v[186:189], v142 offset:32768
	ds_read_b128 v[190:193], v142 offset:33792
	ds_read_b128 v[194:197], v142 offset:34816
	ds_read_b128 v[198:201], v142 offset:35840
	ds_read_b128 v[202:205], v142 offset:36864
	ds_read_b128 v[206:209], v142 offset:37888
	ds_read_b128 v[210:213], v142 offset:38912
	ds_read_b128 v[214:217], v142 offset:39936
	global_load_lds_dwordx4 v[218:219], off
	s_mov_b32 m0, s40
	v_lshl_add_u64 v[218:219], s[34:35], 0, v[132:133]
	global_load_lds_dwordx4 v[218:219], off
	s_waitcnt lgkmcnt(8)
	s_setprio 1
	s_barrier
	s_waitcnt lgkmcnt(0)
	v_mfma_f32_16x16x32_bf16 v[120:123], v[144:147], v[186:189], v[120:123]
	v_mfma_f32_16x16x32_bf16 v[124:127], v[178:181], v[186:189], v[124:127]
	v_mfma_f32_16x16x32_bf16 v[104:107], v[144:147], v[194:197], v[104:107]
	v_mfma_f32_16x16x32_bf16 v[108:111], v[178:181], v[194:197], v[108:111]
	v_mfma_f32_16x16x32_bf16 v[88:91], v[144:147], v[202:205], v[88:91]
	v_mfma_f32_16x16x32_bf16 v[92:95], v[178:181], v[202:205], v[92:95]
	v_mfma_f32_16x16x32_bf16 v[72:75], v[144:147], v[210:213], v[72:75]
	v_mfma_f32_16x16x32_bf16 v[76:79], v[178:181], v[210:213], v[76:79]
	v_mfma_f32_16x16x32_bf16 v[120:123], v[148:151], v[190:193], v[120:123]
	v_mfma_f32_16x16x32_bf16 v[124:127], v[182:185], v[190:193], v[124:127]
	v_mfma_f32_16x16x32_bf16 v[104:107], v[148:151], v[198:201], v[104:107]
	v_mfma_f32_16x16x32_bf16 v[108:111], v[182:185], v[198:201], v[108:111]
	v_mfma_f32_16x16x32_bf16 v[88:91], v[148:151], v[206:209], v[88:91]
	v_mfma_f32_16x16x32_bf16 v[92:95], v[182:185], v[206:209], v[92:95]
	v_mfma_f32_16x16x32_bf16 v[72:75], v[148:151], v[214:217], v[72:75]
	v_mfma_f32_16x16x32_bf16 v[76:79], v[182:185], v[214:217], v[76:79]
	s_setprio 0
	s_barrier
	s_add_i32 s34, 0, 0x1c000
	s_add_i32 s35, s78, s36
	v_add_u32_e32 v143, s34, v140
	v_lshl_add_u64 v[138:139], v[138:139], 0, s[88:89]
	s_mov_b32 m0, s35
	ds_read_b128 v[218:221], v143
	ds_read_b128 v[222:225], v143 offset:1024
	ds_read_b128 v[226:229], v143 offset:2048
	ds_read_b128 v[230:233], v143 offset:3072
	global_load_lds_dwordx4 v[138:139], off
	s_add_i32 m0, s35, 0x2000
	v_lshl_add_u64 v[138:139], v[234:235], 0, s[88:89]
	global_load_lds_dwordx4 v[138:139], off
	s_setprio 1
	s_barrier
	s_waitcnt lgkmcnt(0)
	v_mfma_f32_16x16x32_bf16 v[112:115], v[218:221], v[186:189], v[112:115]
	v_mfma_f32_16x16x32_bf16 v[116:119], v[226:229], v[186:189], v[116:119]
	v_mfma_f32_16x16x32_bf16 v[96:99], v[218:221], v[194:197], v[96:99]
	v_mfma_f32_16x16x32_bf16 v[100:103], v[226:229], v[194:197], v[100:103]
	v_mfma_f32_16x16x32_bf16 v[80:83], v[218:221], v[202:205], v[80:83]
	v_mfma_f32_16x16x32_bf16 v[84:87], v[226:229], v[202:205], v[84:87]
	v_mfma_f32_16x16x32_bf16 v[64:67], v[218:221], v[210:213], v[64:67]
	v_mfma_f32_16x16x32_bf16 v[68:71], v[226:229], v[210:213], v[68:71]
	v_mfma_f32_16x16x32_bf16 v[112:115], v[222:225], v[190:193], v[112:115]
	v_mfma_f32_16x16x32_bf16 v[116:119], v[230:233], v[190:193], v[116:119]
	v_mfma_f32_16x16x32_bf16 v[96:99], v[222:225], v[198:201], v[96:99]
	v_mfma_f32_16x16x32_bf16 v[100:103], v[230:233], v[198:201], v[100:103]
	v_mfma_f32_16x16x32_bf16 v[80:83], v[222:225], v[206:209], v[80:83]
	v_mfma_f32_16x16x32_bf16 v[84:87], v[230:233], v[206:209], v[84:87]
	v_mfma_f32_16x16x32_bf16 v[64:67], v[222:225], v[214:217], v[64:67]
	v_mfma_f32_16x16x32_bf16 v[68:71], v[230:233], v[214:217], v[68:71]
	s_setprio 0
	s_mov_b32 m0, s41
	v_lshl_add_u64 v[138:139], v[236:237], 0, s[88:89]
	s_barrier
	ds_read_b128 v[186:189], v142 offset:49152
	ds_read_b128 v[190:193], v142 offset:50176
	ds_read_b128 v[194:197], v142 offset:51200
	ds_read_b128 v[198:201], v142 offset:52224
	ds_read_b128 v[202:205], v142 offset:53248
	ds_read_b128 v[206:209], v142 offset:54272
	ds_read_b128 v[210:213], v142 offset:55296
	ds_read_b128 v[214:217], v142 offset:56320
	global_load_lds_dwordx4 v[138:139], off
	s_mov_b32 m0, s58
	v_lshl_add_u64 v[138:139], v[238:239], 0, s[88:89]
	global_load_lds_dwordx4 v[138:139], off
	s_setprio 1
	s_barrier
; DI unsigned pk2(float a, float b) { f32x2 v = {a, b}; nbf2 r = __builtin_convertvector(v, nbf2); return __builtin_bit_cast(unsigned, r); }
; #define PG8_STAGE(bufoff, gbase, voff) do { _Pragma("unroll") for (int _i = 0; _i < 2; ++_i) \
;         __builtin_amdgcn_global_load_lds((const unsigned*)((const char*)(gbase) + (voff)[_i]), (LAS unsigned*)(lds + (bufoff) + ldsw + _i * 8192), 16, 0, 0); } while (0)
; #define PG8_LDA(dst, b, h) do { _Pragma("unroll") for (int m = 0; m < 4; ++m) _Pragma("unroll") for (int k = 0; k < 2; ++k) dst[m][k] = *(const LAS bf16x8*)(lds + PG8_SA(b, h) + aoff + m * 2048 + k * 1024); } while (0)
; #define PG8_MMA(ai, bj, At, Bt) do { __builtin_amdgcn_s_setprio(1); _Pragma("unroll") for (int m = 0; m < 4; ++m) _Pragma("unroll") for (int n = 0; n < 2; ++n) _Pragma("unroll") for (int k = 0; k < 2; ++k) \
;         acc[ai][bj][m][n] = __builtin_amdgcn_mfma_f32_16x16x32_bf16(Bt[n][k], At[m][k], acc[ai][bj][m][n], 0, 0, 0); __builtin_amdgcn_s_setprio(0); } while (0)
; template <class Epi, class Sched>
; DI void gemm_phase(LAS unsigned char* lds, const Gemm g, const Sched& S, const Epi& E) {
;     ...
;             PG8_BAR; PG8_WAIT_L(0); PG8_MMA(0, 1, At, B1); PG8_BAR;
;             PG8_LDA(At, 1, 1); PG8_STAGE(PG8_SA(1, 0), a3, voffA);
;             PG8_BAR; PG8_WAIT_L(0); PG8_MMA(1, 0, At, B0); PG8_BAR; PG8_SCHED;
;             PG8_STAGE(PG8_SB(1, 1), b3 + hstep, voffB);
;             PG8_WAIT_V(6); PG8_BAR; PG8_MMA(1, 1, At, B1); PG8_BAR;
;         }
;     DI void operator()(const f32x4 (&acc)[2][2][4][2], const pg8::Unit& u, int wr, int wc, int fr, int fq) const {
;     ...
;                     for (int j = 0; j < 4; j += 2) { const f32x2 g2 = {acc[ai][bj][m][0][j], acc[ai][bj][m][0][j + 1]}, u2 = {acc[ai][bj][m][1][j], acc[ai][bj][m][1][j + 1]};
;                         const f32x2 t2 = g2 * (-1.4426950408889634f); f32x2 e2; e2[0] = __builtin_amdgcn_exp2f(t2[0]); e2[1] = __builtin_amdgcn_exp2f(t2[1]);
;                         const f32x2 d2 = e2 + 1.0f; f32x2 r2; r2[0] = __builtin_amdgcn_rcpf(d2[0]); r2[1] = __builtin_amdgcn_rcpf(d2[1]);
;                         const f32x2 h2 = (g2 * u2) * r2; h[bj * 4 + j] = h2[0]; h[bj * 4 + j + 1] = h2[1]; }
;                 u32x4 w; w.x = pk2(h[0], h[1]); w.y = pk2(h[2], h[3]); w.z = pk2(h[4], h[5]); w.w = pk2(h[6], h[7]);
;                 *(u32x4*)rowp = w; asm volatile("" ::: "memory"); }
	s_waitcnt lgkmcnt(0)
	v_mfma_f32_16x16x32_bf16 v[56:59], v[144:147], v[186:189], v[56:59]
	v_mfma_f32_16x16x32_bf16 v[60:63], v[178:181], v[186:189], v[60:63]
	v_mfma_f32_16x16x32_bf16 v[40:43], v[144:147], v[194:197], v[40:43]
	v_mfma_f32_16x16x32_bf16 v[44:47], v[178:181], v[194:197], v[44:47]
	v_mfma_f32_16x16x32_bf16 v[24:27], v[144:147], v[202:205], v[24:27]
	v_mfma_f32_16x16x32_bf16 v[28:31], v[178:181], v[202:205], v[28:31]
	v_mfma_f32_16x16x32_bf16 v[8:11], v[144:147], v[210:213], v[8:11]
	v_mfma_f32_16x16x32_bf16 v[12:15], v[178:181], v[210:213], v[12:15]
	v_mfma_f32_16x16x32_bf16 v[56:59], v[148:151], v[190:193], v[56:59]
	v_mfma_f32_16x16x32_bf16 v[60:63], v[182:185], v[190:193], v[60:63]
	v_mfma_f32_16x16x32_bf16 v[40:43], v[148:151], v[198:201], v[40:43]
	v_mfma_f32_16x16x32_bf16 v[44:47], v[182:185], v[198:201], v[44:47]
	v_mfma_f32_16x16x32_bf16 v[24:27], v[148:151], v[206:209], v[24:27]
	v_mfma_f32_16x16x32_bf16 v[28:31], v[182:185], v[206:209], v[28:31]
	v_mfma_f32_16x16x32_bf16 v[8:11], v[148:151], v[214:217], v[8:11]
	v_mfma_f32_16x16x32_bf16 v[12:15], v[182:185], v[214:217], v[12:15]
	s_setprio 0
	s_barrier
	s_add_u32 s28, s28, 0x40080
	s_addc_u32 s29, s29, 0
	s_add_i32 s34, s34, s36
	s_mov_b32 m0, s34
	v_lshl_add_u64 v[138:139], s[28:29], 0, v[128:129]
	global_load_lds_dwordx4 v[138:139], off
	s_add_i32 m0, s34, 0x2000
	v_lshl_add_u64 v[138:139], s[28:29], 0, v[132:133]
	global_load_lds_dwordx4 v[138:139], off
	s_waitcnt vmcnt(6)
	s_setprio 1
	s_barrier
	v_mfma_f32_16x16x32_bf16 v[48:51], v[218:221], v[186:189], v[48:51]
	v_mfma_f32_16x16x32_bf16 v[52:55], v[226:229], v[186:189], v[52:55]
	v_mfma_f32_16x16x32_bf16 v[32:35], v[218:221], v[194:197], v[32:35]
	v_mfma_f32_16x16x32_bf16 v[36:39], v[226:229], v[194:197], v[36:39]
	v_mfma_f32_16x16x32_bf16 v[16:19], v[218:221], v[202:205], v[16:19]
	v_mfma_f32_16x16x32_bf16 v[20:23], v[226:229], v[202:205], v[20:23]
	v_mfma_f32_16x16x32_bf16 v[0:3], v[218:221], v[210:213], v[0:3]
	v_mfma_f32_16x16x32_bf16 v[4:7], v[226:229], v[210:213], v[4:7]
	v_mfma_f32_16x16x32_bf16 v[48:51], v[222:225], v[190:193], v[48:51]
	v_mfma_f32_16x16x32_bf16 v[52:55], v[230:233], v[190:193], v[52:55]
	v_mfma_f32_16x16x32_bf16 v[32:35], v[222:225], v[198:201], v[32:35]
	v_mfma_f32_16x16x32_bf16 v[36:39], v[230:233], v[198:201], v[36:39]
	v_mfma_f32_16x16x32_bf16 v[16:19], v[222:225], v[206:209], v[16:19]
	v_mfma_f32_16x16x32_bf16 v[20:23], v[230:233], v[206:209], v[20:23]
	v_mfma_f32_16x16x32_bf16 v[0:3], v[222:225], v[214:217], v[0:3]
	v_mfma_f32_16x16x32_bf16 v[4:7], v[230:233], v[214:217], v[4:7]
	s_setprio 0
	s_add_i32 s77, s77, 2
	s_add_u32 s18, s18, 0x100
	s_addc_u32 s19, s19, 0
	s_add_u32 s74, s74, 0x100
	s_addc_u32 s75, s75, 0
	s_cmp_gt_u32 s77, 13
	s_barrier
	s_cbranch_scc0 .LBB0_822
	v_pk_mul_f32 v[148:149], v[120:121], s[76:77] op_sel_hi:[1,0]
	v_pk_mul_f32 v[120:121], v[124:125], v[120:121]
	v_pk_mul_f32 v[124:125], v[112:113], s[76:77] op_sel_hi:[1,0]
	v_pk_mul_f32 v[112:113], v[116:117], v[112:113]
	v_exp_f32_e32 v124, v124
	v_exp_f32_e32 v125, v125
	v_pk_mul_f32 v[126:127], v[126:127], v[122:123]
	v_pk_mul_f32 v[122:123], v[122:123], s[76:77] op_sel_hi:[1,0]
	v_exp_f32_e32 v148, v148
	v_pk_add_f32 v[124:125], v[124:125], 1.0 op_sel_hi:[1,0]
	v_exp_f32_e32 v149, v149
	v_rcp_f32_e32 v124, v124
	v_rcp_f32_e32 v125, v125
	v_exp_f32_e32 v122, v122
	v_exp_f32_e32 v123, v123
	v_pk_add_f32 v[148:149], v[148:149], 1.0 op_sel_hi:[1,0]
	v_pk_mul_f32 v[116:117], v[112:113], v[124:125]
	v_pk_mul_f32 v[112:113], v[114:115], s[76:77] op_sel_hi:[1,0]
	v_pk_add_f32 v[122:123], v[122:123], 1.0 op_sel_hi:[1,0]
	v_exp_f32_e32 v112, v112
	v_exp_f32_e32 v113, v113
	v_rcp_f32_e32 v148, v148
	v_rcp_f32_e32 v149, v149
	v_rcp_f32_e32 v122, v122
	v_pk_add_f32 v[112:113], v[112:113], 1.0 op_sel_hi:[1,0]
	v_rcp_f32_e32 v123, v123
	v_rcp_f32_e32 v112, v112
	v_rcp_f32_e32 v113, v113
	v_lshl_or_b32 v144, s64, 7, v141
	v_lshl_add_u32 v143, s65, 8, v131
	v_ashrrev_i32_e32 v145, 31, v144
	v_mov_b64_e32 v[138:139], s[72:73]
	v_pk_mul_f32 v[118:119], v[118:119], v[114:115]
	v_mad_i64_i32 v[146:147], s[18:19], v143, s60, v[138:139]
	v_pk_mul_f32 v[120:121], v[120:121], v[148:149]
	v_pk_mul_f32 v[122:123], v[126:127], v[122:123]
	v_pk_mul_f32 v[118:119], v[118:119], v[112:113]
	v_lshlrev_b64 v[112:113], 1, v[144:145]
	v_lshl_add_u64 v[124:125], v[146:147], 0, v[112:113]
	v_cvt_pk_bf16_f32 v114, v120, v121
	v_cvt_pk_bf16_f32 v115, v122, v123
	v_cvt_pk_bf16_f32 v116, v116, v117
	v_cvt_pk_bf16_f32 v117, v118, v119
	global_store_dwordx4 v[124:125], v[114:117], off
	v_pk_mul_f32 v[110:111], v[110:111], v[106:107]
	v_pk_mul_f32 v[106:107], v[106:107], s[76:77] op_sel_hi:[1,0]
	v_pk_mul_f32 v[116:117], v[104:105], s[76:77] op_sel_hi:[1,0]
	v_pk_mul_f32 v[104:105], v[108:109], v[104:105]
	v_pk_mul_f32 v[108:109], v[96:97], s[76:77] op_sel_hi:[1,0]
	v_pk_mul_f32 v[96:97], v[100:101], v[96:97]
	v_exp_f32_e32 v108, v108
	v_exp_f32_e32 v109, v109
	v_exp_f32_e32 v116, v116
	v_exp_f32_e32 v117, v117
	v_exp_f32_e32 v106, v106
	v_pk_add_f32 v[108:109], v[108:109], 1.0 op_sel_hi:[1,0]
	v_exp_f32_e32 v107, v107
	v_rcp_f32_e32 v108, v108
	v_rcp_f32_e32 v109, v109
	v_pk_add_f32 v[116:117], v[116:117], 1.0 op_sel_hi:[1,0]
	v_pk_add_f32 v[106:107], v[106:107], 1.0 op_sel_hi:[1,0]
	v_rcp_f32_e32 v116, v116
	v_pk_mul_f32 v[100:101], v[96:97], v[108:109]
	v_pk_mul_f32 v[96:97], v[98:99], s[76:77] op_sel_hi:[1,0]
	v_rcp_f32_e32 v117, v117
	v_exp_f32_e32 v96, v96
	v_exp_f32_e32 v97, v97
	v_rcp_f32_e32 v106, v106
	v_rcp_f32_e32 v107, v107
	v_or_b32_e32 v114, 16, v143
	v_pk_add_f32 v[96:97], v[96:97], 1.0 op_sel_hi:[1,0]
; DI unsigned pk2(float a, float b) { f32x2 v = {a, b}; nbf2 r = __builtin_convertvector(v, nbf2); return __builtin_bit_cast(unsigned, r); }
;     DI void operator()(const f32x4 (&acc)[2][2][4][2], const pg8::Unit& u, int wr, int wc, int fr, int fq) const {
;     ...
;         for (int ai = 0; ai < 2; ++ai)
; #pragma unroll
;             for (int m = 0; m < 4; ++m) { bf16_t* rowp = H + (size_t)(row0 + ai * 128 + m * 16) * FF + col0;
;                 float h[8];
; #pragma unroll
;                 for (int bj = 0; bj < 2; ++bj)
; #pragma unroll
;                     for (int j = 0; j < 4; j += 2) { const f32x2 g2 = {acc[ai][bj][m][0][j], acc[ai][bj][m][0][j + 1]}, u2 = {acc[ai][bj][m][1][j], acc[ai][bj][m][1][j + 1]};
;                         const f32x2 t2 = g2 * (-1.4426950408889634f); f32x2 e2; e2[0] = __builtin_amdgcn_exp2f(t2[0]); e2[1] = __builtin_amdgcn_exp2f(t2[1]);
;                         const f32x2 d2 = e2 + 1.0f; f32x2 r2; r2[0] = __builtin_amdgcn_rcpf(d2[0]); r2[1] = __builtin_amdgcn_rcpf(d2[1]);
;                         const f32x2 h2 = (g2 * u2) * r2; h[bj * 4 + j] = h2[0]; h[bj * 4 + j + 1] = h2[1]; }
;                 u32x4 w; w.x = pk2(h[0], h[1]); w.y = pk2(h[2], h[3]); w.z = pk2(h[4], h[5]); w.w = pk2(h[6], h[7]);
;                 *(u32x4*)rowp = w; asm volatile("" ::: "memory"); }
	v_pk_mul_f32 v[102:103], v[102:103], v[98:99]
	v_rcp_f32_e32 v96, v96
	v_rcp_f32_e32 v97, v97
	v_mad_i64_i32 v[114:115], s[18:19], v114, s60, v[138:139]
	v_pk_mul_f32 v[104:105], v[104:105], v[116:117]
	v_pk_mul_f32 v[106:107], v[110:111], v[106:107]
	v_pk_mul_f32 v[102:103], v[102:103], v[96:97]
	v_lshl_add_u64 v[108:109], v[114:115], 0, v[112:113]
	v_cvt_pk_bf16_f32 v96, v104, v105
	v_cvt_pk_bf16_f32 v97, v106, v107
	v_cvt_pk_bf16_f32 v98, v100, v101
	v_cvt_pk_bf16_f32 v99, v102, v103
	global_store_dwordx4 v[108:109], v[96:99], off
	v_pk_mul_f32 v[94:95], v[94:95], v[90:91]
	v_pk_mul_f32 v[90:91], v[90:91], s[76:77] op_sel_hi:[1,0]
	v_pk_mul_f32 v[98:99], v[88:89], s[76:77] op_sel_hi:[1,0]
	v_pk_mul_f32 v[88:89], v[92:93], v[88:89]
	v_pk_mul_f32 v[92:93], v[80:81], s[76:77] op_sel_hi:[1,0]
	v_pk_mul_f32 v[80:81], v[84:85], v[80:81]
	v_exp_f32_e32 v92, v92
	v_exp_f32_e32 v93, v93
	v_exp_f32_e32 v98, v98
	v_exp_f32_e32 v99, v99
	v_exp_f32_e32 v90, v90
	v_pk_add_f32 v[92:93], v[92:93], 1.0 op_sel_hi:[1,0]
	v_exp_f32_e32 v91, v91
	v_rcp_f32_e32 v92, v92
	v_rcp_f32_e32 v93, v93
	v_pk_add_f32 v[98:99], v[98:99], 1.0 op_sel_hi:[1,0]
	v_pk_add_f32 v[90:91], v[90:91], 1.0 op_sel_hi:[1,0]
	v_rcp_f32_e32 v98, v98
	v_pk_mul_f32 v[84:85], v[80:81], v[92:93]
	v_pk_mul_f32 v[80:81], v[82:83], s[76:77] op_sel_hi:[1,0]
	v_rcp_f32_e32 v99, v99
	v_exp_f32_e32 v80, v80
	v_exp_f32_e32 v81, v81
	v_rcp_f32_e32 v90, v90
	v_rcp_f32_e32 v91, v91
	v_or_b32_e32 v96, 32, v143
	v_pk_add_f32 v[80:81], v[80:81], 1.0 op_sel_hi:[1,0]
	v_pk_mul_f32 v[86:87], v[86:87], v[82:83]
	v_rcp_f32_e32 v80, v80
	v_rcp_f32_e32 v81, v81
	v_mad_i64_i32 v[96:97], s[18:19], v96, s60, v[138:139]
	v_pk_mul_f32 v[88:89], v[88:89], v[98:99]
	v_pk_mul_f32 v[90:91], v[94:95], v[90:91]
	v_pk_mul_f32 v[86:87], v[86:87], v[80:81]
	v_lshl_add_u64 v[92:93], v[96:97], 0, v[112:113]
	v_cvt_pk_bf16_f32 v80, v88, v89
	v_cvt_pk_bf16_f32 v81, v90, v91
	v_cvt_pk_bf16_f32 v82, v84, v85
	v_cvt_pk_bf16_f32 v83, v86, v87
	global_store_dwordx4 v[92:93], v[80:83], off
	v_pk_mul_f32 v[78:79], v[78:79], v[74:75]
	v_pk_mul_f32 v[74:75], v[74:75], s[76:77] op_sel_hi:[1,0]
	v_pk_mul_f32 v[82:83], v[72:73], s[76:77] op_sel_hi:[1,0]
	v_pk_mul_f32 v[72:73], v[76:77], v[72:73]
	v_pk_mul_f32 v[76:77], v[64:65], s[76:77] op_sel_hi:[1,0]
	v_pk_mul_f32 v[64:65], v[68:69], v[64:65]
	v_exp_f32_e32 v76, v76
	v_exp_f32_e32 v77, v77
	v_exp_f32_e32 v82, v82
	v_exp_f32_e32 v83, v83
	v_exp_f32_e32 v74, v74
	v_pk_add_f32 v[76:77], v[76:77], 1.0 op_sel_hi:[1,0]
	v_exp_f32_e32 v75, v75
	v_rcp_f32_e32 v76, v76
	v_rcp_f32_e32 v77, v77
	v_pk_add_f32 v[82:83], v[82:83], 1.0 op_sel_hi:[1,0]
	v_pk_add_f32 v[74:75], v[74:75], 1.0 op_sel_hi:[1,0]
	v_rcp_f32_e32 v82, v82
	v_pk_mul_f32 v[68:69], v[64:65], v[76:77]
	v_pk_mul_f32 v[64:65], v[66:67], s[76:77] op_sel_hi:[1,0]
	v_rcp_f32_e32 v83, v83
	v_exp_f32_e32 v64, v64
	v_exp_f32_e32 v65, v65
	v_rcp_f32_e32 v74, v74
	v_rcp_f32_e32 v75, v75
	v_or_b32_e32 v80, 48, v143
	v_pk_add_f32 v[64:65], v[64:65], 1.0 op_sel_hi:[1,0]
	v_pk_mul_f32 v[70:71], v[70:71], v[66:67]
	v_rcp_f32_e32 v64, v64
	v_rcp_f32_e32 v65, v65
	v_mad_i64_i32 v[80:81], s[18:19], v80, s60, v[138:139]
	v_pk_mul_f32 v[72:73], v[72:73], v[82:83]
	v_pk_mul_f32 v[74:75], v[78:79], v[74:75]
	v_pk_mul_f32 v[70:71], v[70:71], v[64:65]
	v_lshl_add_u64 v[76:77], v[80:81], 0, v[112:113]
	v_cvt_pk_bf16_f32 v64, v72, v73
	v_cvt_pk_bf16_f32 v65, v74, v75
	v_cvt_pk_bf16_f32 v66, v68, v69
	v_cvt_pk_bf16_f32 v67, v70, v71
	global_store_dwordx4 v[76:77], v[64:67], off
	v_pk_mul_f32 v[62:63], v[62:63], v[58:59]
	v_pk_mul_f32 v[58:59], v[58:59], s[76:77] op_sel_hi:[1,0]
	v_pk_mul_f32 v[66:67], v[56:57], s[76:77] op_sel_hi:[1,0]
	v_pk_mul_f32 v[56:57], v[60:61], v[56:57]
	v_pk_mul_f32 v[60:61], v[48:49], s[76:77] op_sel_hi:[1,0]
	v_pk_mul_f32 v[48:49], v[52:53], v[48:49]
	v_exp_f32_e32 v60, v60
	v_exp_f32_e32 v61, v61
	v_exp_f32_e32 v66, v66
	v_exp_f32_e32 v67, v67
	v_exp_f32_e32 v58, v58
	v_pk_add_f32 v[60:61], v[60:61], 1.0 op_sel_hi:[1,0]
	v_exp_f32_e32 v59, v59
	v_rcp_f32_e32 v60, v60
	v_rcp_f32_e32 v61, v61
	v_pk_add_f32 v[66:67], v[66:67], 1.0 op_sel_hi:[1,0]
	v_pk_add_f32 v[58:59], v[58:59], 1.0 op_sel_hi:[1,0]
	v_rcp_f32_e32 v66, v66
	v_pk_mul_f32 v[52:53], v[48:49], v[60:61]
	v_pk_mul_f32 v[48:49], v[50:51], s[76:77] op_sel_hi:[1,0]
	v_rcp_f32_e32 v67, v67
	v_exp_f32_e32 v48, v48
	v_exp_f32_e32 v49, v49
	v_rcp_f32_e32 v58, v58
	v_rcp_f32_e32 v59, v59
	v_add_u32_e32 v64, 0x80, v143
	v_pk_add_f32 v[48:49], v[48:49], 1.0 op_sel_hi:[1,0]
	v_pk_mul_f32 v[54:55], v[54:55], v[50:51]
	v_rcp_f32_e32 v48, v48
	v_rcp_f32_e32 v49, v49
	v_mad_i64_i32 v[64:65], s[18:19], v64, s60, v[138:139]
	v_pk_mul_f32 v[56:57], v[56:57], v[66:67]
	v_pk_mul_f32 v[58:59], v[62:63], v[58:59]
	v_pk_mul_f32 v[54:55], v[54:55], v[48:49]
	v_lshl_add_u64 v[60:61], v[64:65], 0, v[112:113]
; DI unsigned pk2(float a, float b) { f32x2 v = {a, b}; nbf2 r = __builtin_convertvector(v, nbf2); return __builtin_bit_cast(unsigned, r); }
; template <class Epi, class Sched>
; DI void gemm_phase(LAS unsigned char* lds, const Gemm g, const Sched& S, const Epi& E) {
;     ...
;         if (!has_next) break;
; #pragma unroll
;     DI void operator()(const f32x4 (&acc)[2][2][4][2], const pg8::Unit& u, int wr, int wc, int fr, int fq) const {
;     ...
;         for (int ai = 0; ai < 2; ++ai)
; #pragma unroll
;             for (int m = 0; m < 4; ++m) { bf16_t* rowp = H + (size_t)(row0 + ai * 128 + m * 16) * FF + col0;
;                 float h[8];
; #pragma unroll
;                 for (int bj = 0; bj < 2; ++bj)
; #pragma unroll
;                     for (int j = 0; j < 4; j += 2) { const f32x2 g2 = {acc[ai][bj][m][0][j], acc[ai][bj][m][0][j + 1]}, u2 = {acc[ai][bj][m][1][j], acc[ai][bj][m][1][j + 1]};
;                         const f32x2 t2 = g2 * (-1.4426950408889634f); f32x2 e2; e2[0] = __builtin_amdgcn_exp2f(t2[0]); e2[1] = __builtin_amdgcn_exp2f(t2[1]);
;                         const f32x2 d2 = e2 + 1.0f; f32x2 r2; r2[0] = __builtin_amdgcn_rcpf(d2[0]); r2[1] = __builtin_amdgcn_rcpf(d2[1]);
;                         const f32x2 h2 = (g2 * u2) * r2; h[bj * 4 + j] = h2[0]; h[bj * 4 + j + 1] = h2[1]; }
;                 u32x4 w; w.x = pk2(h[0], h[1]); w.y = pk2(h[2], h[3]); w.z = pk2(h[4], h[5]); w.w = pk2(h[6], h[7]);
;                 *(u32x4*)rowp = w; asm volatile("" ::: "memory"); }
	v_cvt_pk_bf16_f32 v48, v56, v57
	v_cvt_pk_bf16_f32 v49, v58, v59
	v_cvt_pk_bf16_f32 v50, v52, v53
	v_cvt_pk_bf16_f32 v51, v54, v55
	global_store_dwordx4 v[60:61], v[48:51], off
	v_pk_mul_f32 v[46:47], v[46:47], v[42:43]
	v_pk_mul_f32 v[42:43], v[42:43], s[76:77] op_sel_hi:[1,0]
	v_pk_mul_f32 v[50:51], v[40:41], s[76:77] op_sel_hi:[1,0]
	v_pk_mul_f32 v[40:41], v[44:45], v[40:41]
	v_pk_mul_f32 v[44:45], v[32:33], s[76:77] op_sel_hi:[1,0]
	v_pk_mul_f32 v[32:33], v[36:37], v[32:33]
	v_exp_f32_e32 v44, v44
	v_exp_f32_e32 v45, v45
	v_exp_f32_e32 v50, v50
	v_exp_f32_e32 v51, v51
	v_exp_f32_e32 v42, v42
	v_pk_add_f32 v[44:45], v[44:45], 1.0 op_sel_hi:[1,0]
	v_exp_f32_e32 v43, v43
	v_rcp_f32_e32 v44, v44
	v_rcp_f32_e32 v45, v45
	v_pk_add_f32 v[50:51], v[50:51], 1.0 op_sel_hi:[1,0]
	v_pk_add_f32 v[42:43], v[42:43], 1.0 op_sel_hi:[1,0]
	v_rcp_f32_e32 v50, v50
	v_pk_mul_f32 v[36:37], v[32:33], v[44:45]
	v_pk_mul_f32 v[32:33], v[34:35], s[76:77] op_sel_hi:[1,0]
	v_rcp_f32_e32 v51, v51
	v_exp_f32_e32 v32, v32
	v_exp_f32_e32 v33, v33
	v_rcp_f32_e32 v42, v42
	v_rcp_f32_e32 v43, v43
	v_add_u32_e32 v48, 0x90, v143
	v_pk_add_f32 v[32:33], v[32:33], 1.0 op_sel_hi:[1,0]
	v_pk_mul_f32 v[38:39], v[38:39], v[34:35]
	v_rcp_f32_e32 v32, v32
	v_rcp_f32_e32 v33, v33
	v_mad_i64_i32 v[48:49], s[18:19], v48, s60, v[138:139]
	v_pk_mul_f32 v[40:41], v[40:41], v[50:51]
	v_pk_mul_f32 v[42:43], v[46:47], v[42:43]
	v_pk_mul_f32 v[38:39], v[38:39], v[32:33]
	v_lshl_add_u64 v[44:45], v[48:49], 0, v[112:113]
	v_cvt_pk_bf16_f32 v32, v40, v41
	v_cvt_pk_bf16_f32 v33, v42, v43
	v_cvt_pk_bf16_f32 v34, v36, v37
	v_cvt_pk_bf16_f32 v35, v38, v39
	global_store_dwordx4 v[44:45], v[32:35], off
	v_pk_mul_f32 v[30:31], v[30:31], v[26:27]
	v_pk_mul_f32 v[26:27], v[26:27], s[76:77] op_sel_hi:[1,0]
	v_pk_mul_f32 v[34:35], v[24:25], s[76:77] op_sel_hi:[1,0]
	v_pk_mul_f32 v[24:25], v[28:29], v[24:25]
	v_pk_mul_f32 v[28:29], v[16:17], s[76:77] op_sel_hi:[1,0]
	v_pk_mul_f32 v[16:17], v[20:21], v[16:17]
	v_exp_f32_e32 v28, v28
	v_exp_f32_e32 v29, v29
	v_exp_f32_e32 v34, v34
	v_exp_f32_e32 v35, v35
	v_exp_f32_e32 v26, v26
	v_pk_add_f32 v[28:29], v[28:29], 1.0 op_sel_hi:[1,0]
	v_exp_f32_e32 v27, v27
	v_rcp_f32_e32 v28, v28
	v_rcp_f32_e32 v29, v29
	v_pk_add_f32 v[34:35], v[34:35], 1.0 op_sel_hi:[1,0]
	v_pk_add_f32 v[26:27], v[26:27], 1.0 op_sel_hi:[1,0]
	v_rcp_f32_e32 v34, v34
	v_pk_mul_f32 v[20:21], v[16:17], v[28:29]
	v_pk_mul_f32 v[16:17], v[18:19], s[76:77] op_sel_hi:[1,0]
	v_rcp_f32_e32 v35, v35
	v_exp_f32_e32 v16, v16
	v_exp_f32_e32 v17, v17
	v_rcp_f32_e32 v26, v26
	v_rcp_f32_e32 v27, v27
	v_add_u32_e32 v32, 0xa0, v143
	v_pk_add_f32 v[16:17], v[16:17], 1.0 op_sel_hi:[1,0]
	v_pk_mul_f32 v[22:23], v[22:23], v[18:19]
	v_rcp_f32_e32 v16, v16
	v_rcp_f32_e32 v17, v17
	v_mad_i64_i32 v[32:33], s[18:19], v32, s60, v[138:139]
	v_pk_mul_f32 v[24:25], v[24:25], v[34:35]
	v_pk_mul_f32 v[26:27], v[30:31], v[26:27]
	v_pk_mul_f32 v[22:23], v[22:23], v[16:17]
	v_lshl_add_u64 v[28:29], v[32:33], 0, v[112:113]
	v_cvt_pk_bf16_f32 v16, v24, v25
	v_cvt_pk_bf16_f32 v17, v26, v27
	v_cvt_pk_bf16_f32 v18, v20, v21
	v_cvt_pk_bf16_f32 v19, v22, v23
	global_store_dwordx4 v[28:29], v[16:19], off
	v_pk_mul_f32 v[14:15], v[14:15], v[10:11]
	v_pk_mul_f32 v[10:11], v[10:11], s[76:77] op_sel_hi:[1,0]
	v_pk_mul_f32 v[18:19], v[8:9], s[76:77] op_sel_hi:[1,0]
	v_pk_mul_f32 v[8:9], v[12:13], v[8:9]
	v_pk_mul_f32 v[12:13], v[0:1], s[76:77] op_sel_hi:[1,0]
	v_pk_mul_f32 v[0:1], v[4:5], v[0:1]
	v_exp_f32_e32 v12, v12
	v_exp_f32_e32 v13, v13
	v_exp_f32_e32 v18, v18
	v_exp_f32_e32 v19, v19
	v_exp_f32_e32 v10, v10
	v_pk_add_f32 v[12:13], v[12:13], 1.0 op_sel_hi:[1,0]
	v_exp_f32_e32 v11, v11
	v_rcp_f32_e32 v12, v12
	v_rcp_f32_e32 v13, v13
	v_pk_add_f32 v[18:19], v[18:19], 1.0 op_sel_hi:[1,0]
	v_pk_add_f32 v[10:11], v[10:11], 1.0 op_sel_hi:[1,0]
	v_rcp_f32_e32 v18, v18
	v_pk_mul_f32 v[4:5], v[0:1], v[12:13]
	v_pk_mul_f32 v[0:1], v[2:3], s[76:77] op_sel_hi:[1,0]
	v_rcp_f32_e32 v19, v19
	v_exp_f32_e32 v0, v0
	v_exp_f32_e32 v1, v1
	v_rcp_f32_e32 v10, v10
	v_rcp_f32_e32 v11, v11
	v_add_u32_e32 v16, 0xb0, v143
	v_pk_add_f32 v[0:1], v[0:1], 1.0 op_sel_hi:[1,0]
	v_pk_mul_f32 v[6:7], v[6:7], v[2:3]
	v_rcp_f32_e32 v0, v0
	v_rcp_f32_e32 v1, v1
	v_mad_i64_i32 v[16:17], s[18:19], v16, s60, v[138:139]
	v_pk_mul_f32 v[8:9], v[8:9], v[18:19]
	v_pk_mul_f32 v[10:11], v[14:15], v[10:11]
	v_pk_mul_f32 v[6:7], v[6:7], v[0:1]
	v_lshl_add_u64 v[12:13], v[16:17], 0, v[112:113]
	v_cvt_pk_bf16_f32 v0, v8, v9
	v_cvt_pk_bf16_f32 v1, v10, v11
	v_cvt_pk_bf16_f32 v2, v4, v5
	v_cvt_pk_bf16_f32 v3, v6, v7
	global_store_dwordx4 v[12:13], v[0:3], off
	s_and_b64 vcc, exec, s[8:9]
	s_mov_b32 s64, s10
	s_mov_b32 s65, s12
	s_mov_b64 s[28:29], s[16:17]
	s_mov_b64 s[18:19], s[14:15]
	s_cbranch_vccz .LBB0_815
	s_waitcnt vmcnt(0)
	s_cmpk_gt_u32 s2, 0xff
	s_cbranch_scc1 .LBB0_826
	s_barrier
